# cache-policy hint: nt on prep's 28 streaming dwordx4 stores (sc / gate written once, consumed in a later phase), on v51
# speedup vs baseline: 1.0055x; 1.0055x over previous
.LBB0_910:
	s_or_b64 exec, exec, s[46:47]
	v_add_u32_e32 v72, v111, v226
	v_ashrrev_i32_e32 v73, 31, v72
	v_lshrrev_b32_e32 v73, 26, v73
	v_add_u32_e32 v72, v72, v73
	v_ashrrev_i32_e32 v72, 6, v72
	v_cvt_pk_bf16_f32 v86, v66, v67
	v_lshl_add_u32 v66, v72, 3, s52
	v_cvt_pk_bf16_f32 v80, v80, v81
	v_cvt_pk_bf16_f32 v84, v82, v83
	v_cvt_pk_bf16_f32 v81, v78, v79
	v_cvt_pk_bf16_f32 v82, v76, v77
	v_cvt_pk_bf16_f32 v83, v74, v75
	v_ashrrev_i32_e32 v67, 31, v66
	v_cvt_pk_bf16_f32 v85, v70, v71
	v_cvt_pk_bf16_f32 v87, v68, v69
	ds_write_b128 v221, v[80:83]
	ds_write_b128 v221, v[84:87] offset:16
	s_waitcnt lgkmcnt(0)
	s_barrier
	v_lshlrev_b64 v[126:127], 11, v[66:67]
	ds_read_b128 v[66:69], v224
	ds_read_b128 v[82:85], v224 offset:64
	s_waitcnt lgkmcnt(1)
	v_mfma_f32_16x16x32_bf16 v[70:73], v[44:47], v[66:69], 0
	v_add_u32_e32 v132, v218, v225
	v_ashrrev_i32_e32 v133, 31, v132
	s_mov_b64 s[6:7], 0x7800400
	v_mfma_f32_16x16x32_bf16 v[74:77], v[50:53], v[66:69], 0
	v_or_b32_e32 v128, v227, v218
	v_ashrrev_i32_e32 v129, 31, v128
	v_cmp_lt_i32_e32 vcc, 0, v128
	v_mfma_f32_16x16x32_bf16 v[78:81], v[54:57], v[66:69], 0
	s_nop 0
	v_cndmask_b32_e64 v201, 0, -1, vcc
	v_cndmask_b32_e32 v200, 0, v210, vcc
	v_mfma_f32_16x16x32_bf16 v[66:69], v[58:61], v[66:69], 0
	v_cndmask_b32_e64 v176, 0, 1.0, vcc
	s_waitcnt lgkmcnt(0)
	v_mfma_f32_16x16x32_bf16 v[70:73], v[32:35], v[82:85], v[70:73]
	v_mfma_f32_16x16x32_bf16 v[74:77], v[36:39], v[82:85], v[74:77]
	v_mfma_f32_16x16x32_bf16 v[78:81], v[40:43], v[82:85], v[78:81]
	v_mfma_f32_16x16x32_bf16 v[66:69], v[62:65], v[82:85], v[66:69]
	ds_read_b128 v[82:85], v222 offset:45056
	ds_read_b128 v[86:89], v222 offset:45072
	s_waitcnt lgkmcnt(1)
	s_nop 1
	v_add_f32_e32 v70, v70, v82
	v_add_f32_e32 v71, v71, v83
	v_mul_f32_e32 v70, 0xbfb8aa3b, v70
	v_mul_f32_e32 v71, 0xbfb8aa3b, v71
	v_exp_f32_e32 v70, v70
	v_exp_f32_e32 v71, v71
	v_add_f32_e32 v70, 1.0, v70
	v_add_f32_e32 v71, 1.0, v71
	v_rcp_f32_e32 v70, v70
	v_rcp_f32_e32 v71, v71
	s_nop 0
	v_pk_mul_f32 v[160:161], v[70:71], s[72:73] op_sel_hi:[1,0]
	v_add_f32_e32 v70, v72, v84
	v_add_f32_e32 v71, v73, v85
	v_mul_f32_e32 v70, 0xbfb8aa3b, v70
	v_mul_f32_e32 v71, 0xbfb8aa3b, v71
	v_exp_f32_e32 v70, v70
	v_exp_f32_e32 v71, v71
	ds_read_b128 v[82:85], v224 offset:192
	v_add_f32_e32 v70, 1.0, v70
	v_add_f32_e32 v71, 1.0, v71
	v_rcp_f32_e32 v70, v70
	v_rcp_f32_e32 v71, v71
	s_nop 0
	v_pk_mul_f32 v[162:163], v[70:71], s[72:73] op_sel_hi:[1,0]
	s_waitcnt lgkmcnt(1)
	v_add_f32_e32 v70, v74, v86
	v_add_f32_e32 v71, v75, v87
	v_mul_f32_e32 v70, 0xbfb8aa3b, v70
	v_mul_f32_e32 v71, 0xbfb8aa3b, v71
	v_exp_f32_e32 v70, v70
	v_exp_f32_e32 v71, v71
	v_add_f32_e32 v70, 1.0, v70
	v_add_f32_e32 v71, 1.0, v71
	v_rcp_f32_e32 v70, v70
	v_rcp_f32_e32 v71, v71
	s_nop 0
	v_pk_mul_f32 v[164:165], v[70:71], s[72:73] op_sel_hi:[1,0]
	v_add_f32_e32 v70, v76, v88
	v_add_f32_e32 v71, v77, v89
	v_mul_f32_e32 v70, 0xbfb8aa3b, v70
	v_mul_f32_e32 v71, 0xbfb8aa3b, v71
	v_exp_f32_e32 v70, v70
	v_exp_f32_e32 v71, v71
	global_load_dwordx4 v[86:89], v[112:113], off offset:64
	v_add_f32_e32 v70, 1.0, v70
	v_add_f32_e32 v71, 1.0, v71
	v_rcp_f32_e32 v70, v70
	v_rcp_f32_e32 v71, v71
	s_nop 0
	v_pk_mul_f32 v[166:167], v[70:71], s[72:73] op_sel_hi:[1,0]
	ds_read_b128 v[70:73], v222 offset:45184
	s_waitcnt lgkmcnt(0)
	v_add_f32_e32 v70, v78, v70
	v_add_f32_e32 v71, v79, v71
	v_mul_f32_e32 v70, 0xbfb8aa3b, v70
	v_mul_f32_e32 v71, 0xbfb8aa3b, v71
	v_exp_f32_e32 v70, v70
	v_exp_f32_e32 v71, v71
	v_add_f32_e32 v70, 1.0, v70
	v_add_f32_e32 v71, 1.0, v71
	v_rcp_f32_e32 v70, v70
	v_rcp_f32_e32 v71, v71
	s_nop 0
	v_pk_mul_f32 v[150:151], v[70:71], s[72:73] op_sel_hi:[1,0]
	v_add_f32_e32 v70, v80, v72
	v_add_f32_e32 v71, v81, v73
	v_mul_f32_e32 v70, 0xbfb8aa3b, v70
	v_mul_f32_e32 v71, 0xbfb8aa3b, v71
	v_exp_f32_e32 v70, v70
	v_exp_f32_e32 v71, v71
	v_add_f32_e32 v70, 1.0, v70
	v_add_f32_e32 v71, 1.0, v71
	v_rcp_f32_e32 v70, v70
	v_rcp_f32_e32 v71, v71
	s_nop 0
	v_pk_mul_f32 v[152:153], v[70:71], s[72:73] op_sel_hi:[1,0]
	ds_read_b128 v[70:73], v222 offset:45200
	s_waitcnt lgkmcnt(0)
	v_add_f32_e32 v66, v66, v70
	v_add_f32_e32 v67, v67, v71
	v_mul_f32_e32 v66, 0xbfb8aa3b, v66
	v_mul_f32_e32 v67, 0xbfb8aa3b, v67
	v_exp_f32_e32 v66, v66
	v_exp_f32_e32 v67, v67
	v_add_f32_e32 v66, 1.0, v66
	v_add_f32_e32 v67, 1.0, v67
	v_rcp_f32_e32 v66, v66
	v_rcp_f32_e32 v67, v67
	s_nop 0
	v_pk_mul_f32 v[156:157], v[66:67], s[72:73] op_sel_hi:[1,0]
	v_add_f32_e32 v66, v68, v72
	v_add_f32_e32 v67, v69, v73
	v_mul_f32_e32 v66, 0xbfb8aa3b, v66
	v_mul_f32_e32 v67, 0xbfb8aa3b, v67
	v_exp_f32_e32 v66, v66
	v_exp_f32_e32 v67, v67
	v_add_f32_e32 v66, 1.0, v66
	v_add_f32_e32 v67, 1.0, v67
	v_rcp_f32_e32 v66, v66
	v_rcp_f32_e32 v67, v67
	s_nop 0
	v_pk_mul_f32 v[158:159], v[66:67], s[72:73] op_sel_hi:[1,0]
	ds_read_b128 v[66:69], v224 offset:128
	s_waitcnt lgkmcnt(0)
	v_mfma_f32_16x16x32_bf16 v[70:73], v[0:3], v[66:69], 0
	v_mfma_f32_16x16x32_bf16 v[74:77], v[4:7], v[66:69], 0
	v_mfma_f32_16x16x32_bf16 v[78:81], v[8:11], v[66:69], 0
	v_mfma_f32_16x16x32_bf16 v[66:69], v[12:15], v[66:69], 0
	v_mfma_f32_16x16x32_bf16 v[70:73], v[16:19], v[82:85], v[70:73]
	v_mfma_f32_16x16x32_bf16 v[74:77], v[20:23], v[82:85], v[74:77]
	v_mfma_f32_16x16x32_bf16 v[78:81], v[24:27], v[82:85], v[78:81]
	v_mfma_f32_16x16x32_bf16 v[66:69], v[28:31], v[82:85], v[66:69]
	ds_read_b128 v[82:85], v222 offset:47104
	s_waitcnt lgkmcnt(0)
	s_nop 2
	v_add_f32_e32 v70, v70, v82
	v_mul_f32_e32 v70, 0xbfb8aa3b, v70
	v_exp_f32_e32 v70, v70
	s_nop 0
	v_add_f32_e32 v70, 1.0, v70
	v_rcp_f32_e32 v146, v70
	v_add_f32_e32 v70, v71, v83
	v_mul_f32_e32 v70, 0xbfb8aa3b, v70
	v_exp_f32_e32 v70, v70
	s_nop 0
	v_add_f32_e32 v70, 1.0, v70
	v_rcp_f32_e32 v147, v70
	v_add_f32_e32 v70, v72, v84
	v_mul_f32_e32 v70, 0xbfb8aa3b, v70
	v_exp_f32_e32 v70, v70
	s_nop 0
	v_add_f32_e32 v70, 1.0, v70
	v_rcp_f32_e32 v148, v70
	v_add_f32_e32 v70, v73, v85
	v_mul_f32_e32 v70, 0xbfb8aa3b, v70
	v_exp_f32_e32 v70, v70
	global_load_dwordx4 v[82:85], v[118:119], off
	v_add_f32_e32 v70, 1.0, v70
	v_rcp_f32_e32 v149, v70
	ds_read_b128 v[70:73], v222 offset:47120
	s_waitcnt lgkmcnt(0)
	v_add_f32_e32 v70, v74, v70
	v_mul_f32_e32 v70, 0xbfb8aa3b, v70
	v_exp_f32_e32 v70, v70
	s_nop 0
	v_add_f32_e32 v70, 1.0, v70
	v_rcp_f32_e32 v142, v70
	v_add_f32_e32 v70, v75, v71
	v_mul_f32_e32 v70, 0xbfb8aa3b, v70
	v_exp_f32_e32 v70, v70
	s_nop 0
	v_add_f32_e32 v70, 1.0, v70
	v_rcp_f32_e32 v143, v70
	v_add_f32_e32 v70, v76, v72
	v_mul_f32_e32 v70, 0xbfb8aa3b, v70
	v_exp_f32_e32 v70, v70
	s_nop 0
	v_add_f32_e32 v70, 1.0, v70
	v_rcp_f32_e32 v144, v70
	v_add_f32_e32 v70, v77, v73
	v_mul_f32_e32 v70, 0xbfb8aa3b, v70
	v_exp_f32_e32 v70, v70
	global_load_dwordx4 v[74:77], v[114:115], off
	v_add_f32_e32 v70, 1.0, v70
	v_rcp_f32_e32 v145, v70
	ds_read_b128 v[70:73], v222 offset:47232
	s_waitcnt lgkmcnt(0)
	v_add_f32_e32 v70, v78, v70
	v_mul_f32_e32 v70, 0xbfb8aa3b, v70
	v_exp_f32_e32 v70, v70
	s_nop 0
	v_add_f32_e32 v70, 1.0, v70
	v_rcp_f32_e32 v138, v70
	v_add_f32_e32 v70, v79, v71
	v_mul_f32_e32 v70, 0xbfb8aa3b, v70
	v_exp_f32_e32 v70, v70
	s_nop 0
	v_add_f32_e32 v70, 1.0, v70
	v_rcp_f32_e32 v139, v70
	v_add_f32_e32 v70, v80, v72
	v_mul_f32_e32 v70, 0xbfb8aa3b, v70
	v_exp_f32_e32 v70, v70
	s_nop 0
	v_add_f32_e32 v70, 1.0, v70
	v_rcp_f32_e32 v140, v70
	v_add_f32_e32 v70, v81, v73
	v_mul_f32_e32 v70, 0xbfb8aa3b, v70
	v_exp_f32_e32 v70, v70
	global_load_dwordx4 v[78:81], v[116:117], off
	global_load_dwordx4 v[242:245], v[114:115], off offset:64
	global_load_dwordx4 v[246:249], v[116:117], off offset:64
	global_load_dwordx4 v[250:253], v[118:119], off offset:64
	v_add_f32_e32 v70, 1.0, v70
	v_rcp_f32_e32 v141, v70
	ds_read_b128 v[70:73], v222 offset:47248
	s_waitcnt lgkmcnt(0)
	v_add_f32_e32 v66, v66, v70
	v_mul_f32_e32 v66, 0xbfb8aa3b, v66
	v_exp_f32_e32 v66, v66
	s_nop 0
	v_add_f32_e32 v66, 1.0, v66
	v_rcp_f32_e32 v134, v66
	v_add_f32_e32 v66, v67, v71
	v_mul_f32_e32 v66, 0xbfb8aa3b, v66
	v_exp_f32_e32 v66, v66
	s_nop 0
	v_add_f32_e32 v66, 1.0, v66
	v_rcp_f32_e32 v135, v66
	v_add_f32_e32 v66, v68, v72
	v_mul_f32_e32 v66, 0xbfb8aa3b, v66
	v_exp_f32_e32 v66, v66
	s_nop 0
	v_add_f32_e32 v66, 1.0, v66
	v_rcp_f32_e32 v136, v66
	v_add_f32_e32 v66, v69, v73
	global_load_dwordx4 v[70:73], v[112:113], off
	v_mul_f32_e32 v66, 0xbfb8aa3b, v66
	v_exp_f32_e32 v66, v66
	s_nop 0
	v_add_f32_e32 v66, 1.0, v66
	v_rcp_f32_e32 v137, v66
	ds_read_b128 v[66:69], v224 offset:256
	s_waitcnt vmcnt(0) lgkmcnt(0)
	v_mfma_f32_16x16x32_bf16 v[70:73], v[70:73], v[66:69], 0
	v_mfma_f32_16x16x32_bf16 v[74:77], v[74:77], v[66:69], 0
	v_mfma_f32_16x16x32_bf16 v[78:81], v[78:81], v[66:69], 0
	v_mfma_f32_16x16x32_bf16 v[66:69], v[82:85], v[66:69], 0
	ds_read_b128 v[82:85], v224 offset:320
	s_waitcnt lgkmcnt(0)
	v_mfma_f32_16x16x32_bf16 v[70:73], v[86:89], v[82:85], v[70:73]
	global_load_dwordx4 v[86:89], v[112:113], off offset:128
	v_mfma_f32_16x16x32_bf16 v[74:77], v[242:245], v[82:85], v[74:77]
	global_load_dwordx4 v[242:245], v[114:115], off offset:128
	v_mfma_f32_16x16x32_bf16 v[78:81], v[246:249], v[82:85], v[78:81]
	global_load_dwordx4 v[246:249], v[116:117], off offset:128
	v_mfma_f32_16x16x32_bf16 v[66:69], v[250:253], v[82:85], v[66:69]
	global_load_dwordx4 v[250:253], v[118:119], off offset:128
	ds_read_b128 v[82:85], v224 offset:384
	s_waitcnt vmcnt(3) lgkmcnt(0)
	v_mfma_f32_16x16x32_bf16 v[86:89], v[86:89], v[82:85], v[70:73]
	s_waitcnt vmcnt(2)
	v_mfma_f32_16x16x32_bf16 v[90:93], v[242:245], v[82:85], v[74:77]
	s_nop 2
	global_load_dwordx4 v[74:77], v[112:113], off offset:192
	global_load_dwordx4 v[242:245], v[116:117], off offset:192
	s_waitcnt vmcnt(3)
	v_mfma_f32_16x16x32_bf16 v[168:171], v[246:249], v[82:85], v[78:81]
	s_nop 2
	global_load_dwordx4 v[78:81], v[114:115], off offset:192
	global_load_dwordx4 v[246:249], v[118:119], off offset:192
	s_waitcnt vmcnt(4)
	v_mfma_f32_16x16x32_bf16 v[66:69], v[250:253], v[82:85], v[66:69]
	ds_read_b128 v[70:73], v224 offset:448
	s_waitcnt vmcnt(3) lgkmcnt(0)
	v_mfma_f32_16x16x32_bf16 v[74:77], v[74:77], v[70:73], v[86:89]
	s_waitcnt vmcnt(1)
	v_mfma_f32_16x16x32_bf16 v[78:81], v[78:81], v[70:73], v[90:93]
	v_mfma_f32_16x16x32_bf16 v[82:85], v[242:245], v[70:73], v[168:171]
	s_waitcnt vmcnt(0)
	v_mfma_f32_16x16x32_bf16 v[66:69], v[246:249], v[70:73], v[66:69]
	v_lshlrev_b64 v[70:71], 11, v[132:133]
	v_lshl_add_u64 v[70:71], s[2:3], 0, v[70:71]
	v_lshl_add_u64 v[70:71], s[56:57], 1, v[70:71]
	v_lshl_add_u64 v[86:87], v[70:71], 0, v[48:49]
	v_lshl_add_u64 v[88:89], v[86:87], 0, s[6:7]
	v_cvt_pk_bf16_f32 v72, v78, v79
	s_mov_b64 s[6:7], 0x7800440
	v_cvt_pk_bf16_f32 v70, v74, v75
	v_cvt_pk_bf16_f32 v71, v76, v77
	v_cvt_pk_bf16_f32 v73, v80, v81
	global_store_dwordx4 v[88:89], v[70:73], off nt
	s_nop 1
	v_cvt_pk_bf16_f32 v72, v66, v67
	v_lshl_add_u64 v[66:67], v[86:87], 0, s[6:7]
	v_cvt_pk_bf16_f32 v70, v82, v83
	v_cvt_pk_bf16_f32 v71, v84, v85
	v_cvt_pk_bf16_f32 v73, v68, v69
	global_store_dwordx4 v[66:67], v[70:73], off nt
	s_nop 1
	v_lshl_add_u64 v[66:67], v[126:127], 0, v[128:129]
	v_mov_b64_e32 v[68:69], s[54:55]
	v_mad_u64_u32 v[182:183], s[6:7], v66, s95, v[68:69]
	v_mad_i32_i24 v183, v67, s95, v183
	v_mov_b64_e32 v[66:67], s[12:13]
	v_mad_i64_i32 v[202:203], s[6:7], v132, s19, v[66:67]
	v_lshl_add_u64 v[78:79], v[120:121], 1, v[202:203]
	s_mov_b64 s[6:7], 0x800
	v_lshl_add_u64 v[74:75], v[78:79], 0, s[6:7]
	v_lshl_add_u64 v[82:83], v[78:79], 0, v[200:201]
	global_load_dwordx4 v[70:73], v[78:79], off offset:2048
	global_load_dwordx4 v[66:69], v[78:79], off offset:3072
	s_nop 0
	global_load_dwordx4 v[74:77], v[74:75], off offset:2048
	v_lshl_add_u64 v[86:87], v[82:83], 0, s[6:7]
	global_load_dwordx4 v[78:81], v[82:83], off offset:2048
	s_nop 0
	global_load_dwordx4 v[82:85], v[82:83], off offset:3072
	s_nop 0
	global_load_dwordx4 v[86:89], v[86:87], off offset:2048
	ds_read_b128 v[170:173], v223 offset:32768
	ds_read_b128 v[90:93], v223 offset:32784
	ds_read_b128 v[178:181], v223 offset:34816
	ds_read_b128 v[184:187], v223 offset:36864
	v_lshl_add_u64 v[182:183], v[182:183], 0, v[48:49]
	s_mov_b64 s[6:7], 0x280
	s_waitcnt vmcnt(5)
	v_lshlrev_b32_e32 v174, 16, v70
	v_and_b32_e32 v175, 0xffff0000, v70
	v_lshlrev_b32_e32 v70, 16, v71
	v_and_b32_e32 v71, 0xffff0000, v71
	s_waitcnt vmcnt(2)
	v_lshlrev_b32_e32 v168, 16, v78
	v_and_b32_e32 v169, 0xffff0000, v78
	v_xor_b32_e32 v197, 0x80000000, v175
	v_xor_b32_e32 v196, 0x80000000, v174
	v_lshlrev_b32_e32 v78, 16, v79
	v_and_b32_e32 v79, 0xffff0000, v79
	v_pk_fma_f32 v[196:197], v[176:177], v[168:169], v[196:197] op_sel_hi:[0,1,1]
	v_xor_b32_e32 v169, 0x80000000, v71
	v_xor_b32_e32 v168, 0x80000000, v70
	v_lshlrev_b32_e32 v188, 16, v66
	v_and_b32_e32 v189, 0xffff0000, v66
	v_lshlrev_b32_e32 v66, 16, v67
	v_and_b32_e32 v67, 0xffff0000, v67
	v_pk_fma_f32 v[78:79], v[176:177], v[78:79], v[168:169] op_sel_hi:[0,1,1]
	s_waitcnt vmcnt(1)
	v_lshlrev_b32_e32 v192, 16, v82
	v_and_b32_e32 v193, 0xffff0000, v82
	v_lshlrev_b32_e32 v82, 16, v83
	v_and_b32_e32 v83, 0xffff0000, v83
	s_waitcnt lgkmcnt(3)
	v_pk_fma_f32 v[168:169], v[172:173], v[78:79], v[70:71]
	v_xor_b32_e32 v71, 0x80000000, v189
	v_xor_b32_e32 v70, 0x80000000, v188
	v_xor_b32_e32 v79, 0x80000000, v67
	v_xor_b32_e32 v78, 0x80000000, v66
	v_pk_fma_f32 v[70:71], v[176:177], v[192:193], v[70:71] op_sel_hi:[0,1,1]
	v_pk_fma_f32 v[78:79], v[176:177], v[82:83], v[78:79] op_sel_hi:[0,1,1]
	v_pk_fma_f32 v[170:171], v[170:171], v[196:197], v[174:175]
	s_waitcnt lgkmcnt(1)
	v_pk_fma_f32 v[172:173], v[180:181], v[78:79], v[66:67]
	v_pk_fma_f32 v[174:175], v[178:179], v[70:71], v[188:189]
	ds_read_b128 v[178:181], v223 offset:38912
	v_lshlrev_b32_e32 v190, 16, v74
	v_and_b32_e32 v191, 0xffff0000, v74
	v_lshlrev_b32_e32 v74, 16, v75
	v_and_b32_e32 v75, 0xffff0000, v75
	s_waitcnt vmcnt(0)
	v_lshlrev_b32_e32 v194, 16, v86
	v_and_b32_e32 v195, 0xffff0000, v86
	v_xor_b32_e32 v67, 0x80000000, v191
	v_xor_b32_e32 v66, 0x80000000, v190
	v_lshlrev_b32_e32 v86, 16, v87
	v_and_b32_e32 v87, 0xffff0000, v87
	v_pk_fma_f32 v[70:71], v[176:177], v[194:195], v[66:67] op_sel_hi:[0,1,1]
	v_xor_b32_e32 v67, 0x80000000, v75
	v_xor_b32_e32 v66, 0x80000000, v74
	v_pk_fma_f32 v[66:67], v[176:177], v[86:87], v[66:67] op_sel_hi:[0,1,1]
	s_waitcnt lgkmcnt(0)
	v_pk_mul_f32 v[178:179], v[178:179], v[174:175]
	v_pk_mul_f32 v[180:181], v[180:181], v[172:173]
	v_pk_fma_f32 v[66:67], v[186:187], v[66:67], v[74:75]
	v_pk_mul_f32 v[74:75], v[180:181], v[180:181]
	v_pk_mul_f32 v[78:79], v[178:179], v[178:179]
	v_lshlrev_b32_e32 v86, 16, v72
	v_pk_mov_b32 v[82:83], v[78:79], v[74:75] op_sel:[1,0]
	v_mov_b32_e32 v79, v75
	v_pk_add_f32 v[74:75], v[82:83], v[78:79]
	v_and_b32_e32 v87, 0xffff0000, v72
	v_pk_fma_f32 v[70:71], v[184:185], v[70:71], v[190:191]
	v_pk_add_f32 v[192:193], v[74:75], v[74:75] op_sel_hi:[0,1]
	v_lshlrev_b32_e32 v184, 16, v73
	v_and_b32_e32 v185, 0xffff0000, v73
	v_lshlrev_b32_e32 v190, 16, v68
	v_and_b32_e32 v191, 0xffff0000, v68
	v_lshlrev_b32_e32 v188, 16, v69
	v_and_b32_e32 v189, 0xffff0000, v69
	v_lshlrev_b32_e32 v68, 16, v76
	v_and_b32_e32 v69, 0xffff0000, v76
	v_lshlrev_b32_e32 v72, 16, v77
	v_and_b32_e32 v73, 0xffff0000, v77
	v_lshlrev_b32_e32 v186, 16, v80
	v_and_b32_e32 v187, 0xffff0000, v80
	v_lshlrev_b32_e32 v76, 16, v88
	v_and_b32_e32 v77, 0xffff0000, v88
	v_lshlrev_b32_e32 v74, 16, v89
	v_and_b32_e32 v75, 0xffff0000, v89
	v_xor_b32_e32 v89, 0x80000000, v87
	v_xor_b32_e32 v88, 0x80000000, v86
	v_lshlrev_b32_e32 v194, 16, v81
	v_and_b32_e32 v195, 0xffff0000, v81
	v_lshlrev_b32_e32 v196, 16, v84
	v_and_b32_e32 v197, 0xffff0000, v84
	v_lshlrev_b32_e32 v198, 16, v85
	v_and_b32_e32 v199, 0xffff0000, v85
	ds_read_b128 v[78:81], v223 offset:34832
	ds_read_b128 v[82:85], v223 offset:36880
	v_pk_fma_f32 v[88:89], v[176:177], v[186:187], v[88:89] op_sel_hi:[0,1,1]
	v_xor_b32_e32 v187, 0x80000000, v185
	v_xor_b32_e32 v186, 0x80000000, v184
	v_pk_fma_f32 v[186:187], v[176:177], v[194:195], v[186:187] op_sel_hi:[0,1,1]
	v_pk_fma_f32 v[184:185], v[92:93], v[186:187], v[184:185]
	v_pk_fma_f32 v[186:187], v[90:91], v[88:89], v[86:87]
	v_xor_b32_e32 v87, 0x80000000, v191
	v_xor_b32_e32 v86, 0x80000000, v190
	v_pk_fma_f32 v[86:87], v[176:177], v[196:197], v[86:87] op_sel_hi:[0,1,1]
	s_waitcnt lgkmcnt(1)
	v_pk_fma_f32 v[190:191], v[78:79], v[86:87], v[190:191]
	v_xor_b32_e32 v79, 0x80000000, v69
	v_xor_b32_e32 v78, 0x80000000, v68
	v_pk_fma_f32 v[76:77], v[176:177], v[76:77], v[78:79] op_sel_hi:[0,1,1]
	v_xor_b32_e32 v79, 0x80000000, v73
	v_xor_b32_e32 v78, 0x80000000, v72
	v_pk_fma_f32 v[74:75], v[176:177], v[74:75], v[78:79] op_sel_hi:[0,1,1]
	s_waitcnt lgkmcnt(0)
	v_pk_fma_f32 v[78:79], v[84:85], v[74:75], v[72:73]
	ds_read_b128 v[72:75], v223 offset:38928
	v_xor_b32_e32 v89, 0x80000000, v189
	v_xor_b32_e32 v88, 0x80000000, v188
	v_pk_fma_f32 v[88:89], v[176:177], v[198:199], v[88:89] op_sel_hi:[0,1,1]
	v_pk_fma_f32 v[188:189], v[80:81], v[88:89], v[188:189]
	s_waitcnt lgkmcnt(0)
	v_pk_mul_f32 v[194:195], v[72:73], v[190:191]
	v_pk_mul_f32 v[196:197], v[74:75], v[188:189]
	v_pk_fma_f32 v[76:77], v[82:83], v[76:77], v[68:69]
	v_pk_mul_f32 v[68:69], v[196:197], v[196:197]
	v_pk_mul_f32 v[72:73], v[194:195], v[194:195]
	s_nop 0
	v_pk_mov_b32 v[74:75], v[72:73], v[68:69] op_sel:[1,0]
	v_mov_b32_e32 v73, v69
	v_pk_add_f32 v[68:69], v[74:75], v[72:73]
	v_lshl_add_u64 v[72:73], v[182:183], 0, s[6:7]
	v_pk_add_f32 v[198:199], v[68:69], v[68:69] op_sel_hi:[0,1]
	v_cvt_pk_bf16_f32 v68, v70, v71
	v_cvt_pk_bf16_f32 v69, v66, v67
	v_cvt_pk_bf16_f32 v70, v76, v77
	v_cvt_pk_bf16_f32 v71, v78, v79
	global_store_dwordx4 v[72:73], v[68:71], off nt
	s_nop 1
	s_mov_b64 s[6:7], 0x200
	v_lshl_add_u64 v[70:71], v[182:183], 0, s[6:7]
	v_cvt_pk_bf16_f32 v66, v170, v171
	v_cvt_pk_bf16_f32 v67, v168, v169
	v_cvt_pk_bf16_f32 v68, v186, v187
	v_cvt_pk_bf16_f32 v69, v184, v185
	global_store_dwordx4 v[70:71], v[66:69], off nt
	s_nop 1
	v_lshl_add_u64 v[78:79], v[122:123], 1, v[202:203]
	s_mov_b64 s[6:7], 0x840
	v_cvt_pk_bf16_f32 v66, v160, v161
	v_cvt_pk_bf16_f32 v67, v162, v163
	v_cvt_pk_bf16_f32 v68, v164, v165
	v_cvt_pk_bf16_f32 v69, v166, v167
	global_store_dwordx4 v[182:183], v[66:69], off nt
	s_nop 1
	v_lshl_add_u64 v[74:75], v[78:79], 0, s[6:7]
	v_lshl_add_u64 v[82:83], v[78:79], 0, v[200:201]
	global_load_dwordx4 v[66:69], v[78:79], off offset:2112
	global_load_dwordx4 v[70:73], v[78:79], off offset:3136
	s_nop 0
	global_load_dwordx4 v[74:77], v[74:75], off offset:2048
	v_lshl_add_u64 v[86:87], v[82:83], 0, s[6:7]
	global_load_dwordx4 v[78:81], v[82:83], off offset:2112
	s_nop 0
	global_load_dwordx4 v[82:85], v[82:83], off offset:3136
	s_nop 0
	global_load_dwordx4 v[86:89], v[86:87], off offset:2048
	ds_read_b128 v[160:163], v223 offset:32896
	ds_read_b128 v[90:93], v223 offset:32912
	ds_read_b128 v[164:167], v223 offset:34944
	ds_read_b128 v[200:203], v223 offset:36992
	s_mov_b64 s[6:7], 0x2c0
	s_waitcnt vmcnt(5)
	v_lshlrev_b32_e32 v212, 16, v66
	v_and_b32_e32 v213, 0xffff0000, v66
	v_lshlrev_b32_e32 v66, 16, v67
	v_and_b32_e32 v67, 0xffff0000, v67
	s_waitcnt vmcnt(4)
	v_lshlrev_b32_e32 v214, 16, v70
	v_and_b32_e32 v215, 0xffff0000, v70
	v_lshlrev_b32_e32 v228, 16, v71
	v_and_b32_e32 v229, 0xffff0000, v71
	s_waitcnt vmcnt(2)
	v_lshlrev_b32_e32 v70, 16, v78
	v_and_b32_e32 v71, 0xffff0000, v78
	v_xor_b32_e32 v237, 0x80000000, v213
	v_xor_b32_e32 v236, 0x80000000, v212
	v_lshlrev_b32_e32 v230, 16, v74
	v_and_b32_e32 v231, 0xffff0000, v74
	v_lshlrev_b32_e32 v232, 16, v75
	v_and_b32_e32 v233, 0xffff0000, v75
	v_lshlrev_b32_e32 v74, 16, v79
	v_and_b32_e32 v75, 0xffff0000, v79
	v_pk_fma_f32 v[70:71], v[176:177], v[70:71], v[236:237] op_sel_hi:[0,1,1]
	v_xor_b32_e32 v237, 0x80000000, v67
	v_xor_b32_e32 v236, 0x80000000, v66
	v_pk_fma_f32 v[74:75], v[176:177], v[74:75], v[236:237] op_sel_hi:[0,1,1]
	s_waitcnt vmcnt(1)
	v_lshlrev_b32_e32 v78, 16, v82
	v_and_b32_e32 v79, 0xffff0000, v82
	v_lshlrev_b32_e32 v82, 16, v83
	v_and_b32_e32 v83, 0xffff0000, v83
	s_waitcnt lgkmcnt(3)
	v_pk_fma_f32 v[66:67], v[162:163], v[74:75], v[66:67]
	v_xor_b32_e32 v75, 0x80000000, v229
	v_xor_b32_e32 v74, 0x80000000, v228
	s_waitcnt vmcnt(0)
	v_lshlrev_b32_e32 v234, 16, v86
	v_and_b32_e32 v235, 0xffff0000, v86
	v_lshlrev_b32_e32 v86, 16, v87
	v_and_b32_e32 v87, 0xffff0000, v87
	v_pk_fma_f32 v[70:71], v[160:161], v[70:71], v[212:213]
	v_pk_fma_f32 v[82:83], v[176:177], v[82:83], v[74:75] op_sel_hi:[0,1,1]
	v_xor_b32_e32 v75, 0x80000000, v215
	v_xor_b32_e32 v74, 0x80000000, v214
	v_xor_b32_e32 v161, 0x80000000, v233
	v_xor_b32_e32 v160, 0x80000000, v232
	v_pk_fma_f32 v[74:75], v[176:177], v[78:79], v[74:75] op_sel_hi:[0,1,1]
	v_pk_fma_f32 v[86:87], v[176:177], v[86:87], v[160:161] op_sel_hi:[0,1,1]
	v_lshlrev_b32_e32 v212, 16, v68
	v_and_b32_e32 v213, 0xffff0000, v68
	s_waitcnt lgkmcnt(1)
	v_pk_fma_f32 v[74:75], v[164:165], v[74:75], v[214:215]
	v_pk_fma_f32 v[78:79], v[166:167], v[82:83], v[228:229]
	v_xor_b32_e32 v83, 0x80000000, v231
	v_xor_b32_e32 v82, 0x80000000, v230
	s_waitcnt lgkmcnt(0)
	v_pk_fma_f32 v[160:161], v[202:203], v[86:87], v[232:233]
	v_lshlrev_b32_e32 v68, 16, v69
	v_and_b32_e32 v69, 0xffff0000, v69
	v_lshlrev_b32_e32 v214, 16, v72
	v_and_b32_e32 v215, 0xffff0000, v72
	v_lshlrev_b32_e32 v232, 16, v73
	v_and_b32_e32 v233, 0xffff0000, v73
	v_lshlrev_b32_e32 v72, 16, v80
	v_and_b32_e32 v73, 0xffff0000, v80
	v_xor_b32_e32 v241, 0x80000000, v213
	v_xor_b32_e32 v240, 0x80000000, v212
	v_pk_fma_f32 v[82:83], v[176:177], v[234:235], v[82:83] op_sel_hi:[0,1,1]
	v_lshlrev_b32_e32 v234, 16, v76
	v_and_b32_e32 v235, 0xffff0000, v76
	v_lshlrev_b32_e32 v236, 16, v77
	v_and_b32_e32 v237, 0xffff0000, v77
	v_lshlrev_b32_e32 v76, 16, v81
	v_and_b32_e32 v77, 0xffff0000, v81
	v_pk_fma_f32 v[72:73], v[176:177], v[72:73], v[240:241] op_sel_hi:[0,1,1]
	v_xor_b32_e32 v241, 0x80000000, v69
	v_xor_b32_e32 v240, 0x80000000, v68
	v_pk_fma_f32 v[162:163], v[200:201], v[82:83], v[230:231]
	ds_read_b128 v[164:167], v223 offset:39040
	ds_read_b128 v[200:203], v223 offset:34960
	ds_read_b128 v[228:231], v223 offset:37008
	v_pk_fma_f32 v[76:77], v[176:177], v[76:77], v[240:241] op_sel_hi:[0,1,1]
	v_lshlrev_b32_e32 v80, 16, v84
	v_and_b32_e32 v81, 0xffff0000, v84
	v_lshlrev_b32_e32 v84, 16, v85
	v_and_b32_e32 v85, 0xffff0000, v85
	v_pk_fma_f32 v[68:69], v[92:93], v[76:77], v[68:69]
	v_xor_b32_e32 v77, 0x80000000, v233
	v_xor_b32_e32 v76, 0x80000000, v232
	v_pk_fma_f32 v[84:85], v[176:177], v[84:85], v[76:77] op_sel_hi:[0,1,1]
	v_xor_b32_e32 v77, 0x80000000, v215
	v_xor_b32_e32 v76, 0x80000000, v214
	v_pk_fma_f32 v[76:77], v[176:177], v[80:81], v[76:77] op_sel_hi:[0,1,1]
	s_waitcnt lgkmcnt(1)
	v_pk_fma_f32 v[76:77], v[200:201], v[76:77], v[214:215]
	v_pk_fma_f32 v[80:81], v[202:203], v[84:85], v[232:233]
	ds_read_b128 v[200:203], v223 offset:39056
	v_pk_mul_f32 v[86:87], v[164:165], v[74:75]
	v_pk_mul_f32 v[82:83], v[166:167], v[78:79]
	v_mul_f32_e32 v164, v86, v86
	v_pk_fma_f32 v[164:165], v[86:87], v[86:87], v[164:165] op_sel_hi:[1,1,0]
	v_lshlrev_b32_e32 v238, 16, v88
	v_and_b32_e32 v239, 0xffff0000, v88
	v_lshlrev_b32_e32 v88, 16, v89
	v_and_b32_e32 v89, 0xffff0000, v89
	v_pk_fma_f32 v[72:73], v[90:91], v[72:73], v[212:213]
	v_xor_b32_e32 v85, 0x80000000, v235
	v_xor_b32_e32 v84, 0x80000000, v234
	v_xor_b32_e32 v91, 0x80000000, v237
	v_xor_b32_e32 v90, 0x80000000, v236
	v_mul_f32_e32 v164, v82, v82
	v_pk_fma_f32 v[84:85], v[176:177], v[238:239], v[84:85] op_sel_hi:[0,1,1]
	v_pk_fma_f32 v[88:89], v[176:177], v[88:89], v[90:91] op_sel_hi:[0,1,1]
	v_pk_fma_f32 v[166:167], v[82:83], v[82:83], v[164:165] op_sel_hi:[1,1,0]
	s_waitcnt lgkmcnt(1)
	v_pk_fma_f32 v[90:91], v[230:231], v[88:89], v[236:237]
	v_pk_fma_f32 v[92:93], v[228:229], v[84:85], v[234:235]
	s_waitcnt lgkmcnt(0)
	v_pk_mul_f32 v[84:85], v[202:203], v[80:81]
	v_pk_mul_f32 v[88:89], v[200:201], v[76:77]
	v_mul_f32_e32 v164, v84, v84
	v_mul_f32_e32 v192, v88, v88
	v_mul_f32_e32 v198, v89, v89
	v_mul_f32_e32 v166, v85, v85
	v_pk_add_f32 v[192:193], v[192:193], v[198:199]
	v_pk_add_f32 v[164:165], v[164:165], v[166:167]
	v_lshl_add_u64 v[166:167], v[182:183], 0, s[6:7]
	v_pk_add_f32 v[164:165], v[192:193], v[164:165]
	v_cvt_pk_bf16_f32 v162, v162, v163
	v_add_f32_e32 v129, v164, v165
	v_cvt_pk_bf16_f32 v163, v160, v161
	v_cvt_pk_bf16_f32 v164, v92, v93
	v_cvt_pk_bf16_f32 v165, v90, v91
	global_store_dwordx4 v[166:167], v[162:165], off nt
	s_nop 1
	s_mov_b64 s[6:7], 0x240
	v_cvt_pk_bf16_f32 v91, v66, v67
	v_lshl_add_u64 v[160:161], v[182:183], 0, s[6:7]
	v_cvt_pk_bf16_f32 v90, v70, v71
	v_cvt_pk_bf16_f32 v92, v72, v73
	v_cvt_pk_bf16_f32 v93, v68, v69
	global_store_dwordx4 v[160:161], v[90:93], off nt
	s_nop 1
	v_cvt_pk_bf16_f32 v91, v152, v153
	v_lshl_add_u64 v[160:161], v[182:183], 0, 64
	v_cvt_pk_bf16_f32 v90, v150, v151
	v_cvt_pk_bf16_f32 v92, v156, v157
	v_cvt_pk_bf16_f32 v93, v158, v159
	global_store_dwordx4 v[160:161], v[90:93], off nt
	s_nop 1
	v_and_b32_e32 v91, 64, v205
	v_xor_b32_e32 v90, 16, v205
	v_add_u32_e32 v91, 64, v91
	v_cmp_lt_i32_e32 vcc, v90, v91
	s_mov_b32 s6, 0xf800000
	v_pk_add_f32 v[166:167], v[148:149], -1.0 op_sel_hi:[1,0]
	v_cndmask_b32_e32 v90, v205, v90, vcc
	v_lshlrev_b32_e32 v131, 2, v90
	s_waitcnt lgkmcnt(0)
	v_mov_b32_e32 v90, v129
	s_nop 1
	v_permlane16_swap_b32_e32 v129, v90
	v_add_f32_e32 v90, v129, v90
	v_mov_b32_e32 v91, v90
	s_nop 1
	v_permlane32_swap_b32_e32 v90, v91
	v_add_f32_e32 v90, v90, v91
	v_cmp_gt_f32_e32 vcc, s6, v90
	v_mul_f32_e32 v91, 0x4f800000, v90
	s_nop 0
	v_cndmask_b32_e32 v90, v90, v91, vcc
	v_sqrt_f32_e32 v91, v90
	s_nop 0
	v_add_u32_e32 v92, -1, v91
	v_fma_f32 v93, -v92, v91, v90
	v_cmp_ge_f32_e64 s[46:47], 0, v93
	v_add_u32_e32 v93, 1, v91
	s_nop 0
	v_cndmask_b32_e64 v92, v91, v92, s[46:47]
	v_fma_f32 v91, -v93, v91, v90
	v_cmp_lt_f32_e64 s[46:47], 0, v91
	s_nop 1
	v_cndmask_b32_e64 v91, v92, v93, s[46:47]
	v_mul_f32_e32 v92, 0x37800000, v91
	v_cndmask_b32_e32 v91, v91, v92, vcc
	v_cmp_class_f32_e32 vcc, v90, v207
	s_nop 1
	v_cndmask_b32_e32 v90, v91, v90, vcc
	v_max_f32_e32 v90, 0x2b8cbccc, v90
	v_div_scale_f32 v91, s[6:7], v90, v90, 1.0
	v_rcp_f32_e32 v92, v91
	s_mov_b64 s[6:7], 0x180
	v_fma_f32 v93, -v91, v92, 1.0
	v_fmac_f32_e32 v92, v93, v92
	v_div_scale_f32 v93, vcc, 1.0, v90, 1.0
	v_mul_f32_e32 v129, v93, v92
	v_fma_f32 v150, -v91, v129, v93
	v_fmac_f32_e32 v129, v150, v92
	v_fma_f32 v91, -v91, v129, v93
	v_div_fmas_f32 v91, v91, v92, v129
	v_div_fixup_f32 v160, v91, v90, 1.0
	ds_read_b128 v[90:93], v223 offset:40960
	ds_read_b128 v[150:153], v223 offset:40976
	ds_read_b128 v[156:159], v223 offset:43008
	v_pk_mul_f32 v[162:163], v[178:179], v[160:161] op_sel_hi:[1,0]
	v_pk_add_f32 v[178:179], v[146:147], -1.0 op_sel_hi:[1,0]
	s_waitcnt lgkmcnt(2)
	v_pk_fma_f32 v[92:93], v[166:167], v[92:93], 1.0 op_sel_hi:[1,1,0]
	v_pk_fma_f32 v[90:91], v[178:179], v[90:91], 1.0 op_sel_hi:[1,1,0]
	v_pk_mul_f32 v[166:167], v[172:173], v[92:93]
	v_pk_mul_f32 v[172:173], v[174:175], v[90:91]
	v_pk_mul_f32 v[92:93], v[168:169], v[166:167]
	v_pk_mul_f32 v[90:91], v[170:171], v[172:173]
	s_waitcnt lgkmcnt(0)
	v_pk_mul_f32 v[92:93], v[158:159], v[92:93]
	v_pk_mul_f32 v[90:91], v[156:157], v[90:91]
	v_pk_mul_f32 v[164:165], v[180:181], v[160:161] op_sel_hi:[1,0]
	v_add_f32_e32 v90, v90, v91
	v_add_f32_e32 v91, v92, v93
	v_add_f32_e32 v90, v90, v91
	v_add_f32_e32 v129, 0, v90
	ds_read_b128 v[90:93], v223 offset:43024
	v_xor_b32_e32 v161, 0x80000000, v165
	v_xor_b32_e32 v168, 0x80000000, v164
	v_xor_b32_e32 v169, 0x80000000, v163
	v_xor_b32_e32 v170, 0x80000000, v162
	v_pk_mul_f32 v[148:149], v[148:149], v[164:165]
	v_pk_mul_f32 v[146:147], v[146:147], v[162:163]
	v_pk_add_f32 v[162:163], v[144:145], -1.0 op_sel_hi:[1,0]
	v_pk_add_f32 v[164:165], v[142:143], -1.0 op_sel_hi:[1,0]
	v_pk_fma_f32 v[152:153], v[162:163], v[152:153], 1.0 op_sel_hi:[1,1,0]
	v_pk_fma_f32 v[150:151], v[164:165], v[150:151], 1.0 op_sel_hi:[1,1,0]
	v_pk_mul_f32 v[152:153], v[188:189], v[152:153]
	v_pk_mul_f32 v[150:151], v[190:191], v[150:151]
	v_pk_mul_f32 v[164:165], v[184:185], v[152:153]
	v_pk_mul_f32 v[162:163], v[186:187], v[150:151]
	s_waitcnt lgkmcnt(0)
	v_pk_mul_f32 v[92:93], v[92:93], v[164:165]
	v_pk_mul_f32 v[90:91], v[90:91], v[162:163]
	v_pk_mul_f32 v[156:157], v[194:195], v[160:161] op_sel_hi:[1,0]
	v_add_f32_e32 v90, v90, v91
	v_add_f32_e32 v91, v92, v93
	v_pk_mul_f32 v[158:159], v[196:197], v[160:161] op_sel_hi:[1,0]
	v_add_f32_e32 v90, v90, v91
	v_add_f32_e32 v129, v129, v90
	v_xor_b32_e32 v162, 0x80000000, v159
	v_xor_b32_e32 v163, 0x80000000, v158
	v_xor_b32_e32 v164, 0x80000000, v157
	v_xor_b32_e32 v165, 0x80000000, v156
	v_pk_mul_f32 v[142:143], v[142:143], v[156:157]
	v_lshl_add_u64 v[156:157], v[182:183], 0, s[30:31]
	v_cvt_pk_bf16_f32 v90, v172, v173
	v_cvt_pk_bf16_f32 v91, v166, v167
	v_cvt_pk_bf16_f32 v92, v150, v151
	v_cvt_pk_bf16_f32 v93, v152, v153
	global_store_dwordx4 v[156:157], v[90:93], off nt
	s_nop 1
	v_pk_mul_f32 v[144:145], v[144:145], v[158:159]
	v_lshl_add_u64 v[150:151], v[182:183], 0, s[34:35]
	v_cvt_pk_bf16_f32 v90, v170, v169
	v_cvt_pk_bf16_f32 v91, v168, v161
	v_cvt_pk_bf16_f32 v92, v165, v164
	v_cvt_pk_bf16_f32 v93, v163, v162
	global_store_dwordx4 v[150:151], v[90:93], off nt
	s_nop 1
	v_lshl_add_u64 v[150:151], v[182:183], 0, s[6:7]
	v_cvt_pk_bf16_f32 v90, v146, v147
	v_cvt_pk_bf16_f32 v91, v148, v149
	v_cvt_pk_bf16_f32 v92, v142, v143
	v_cvt_pk_bf16_f32 v93, v144, v145
	global_store_dwordx4 v[150:151], v[90:93], off nt
	s_nop 1
	ds_read_b128 v[90:93], v223 offset:41088
	ds_read_b128 v[142:145], v223 offset:41104
	ds_read_b128 v[146:149], v223 offset:43136
	v_pk_add_f32 v[150:151], v[140:141], -1.0 op_sel_hi:[1,0]
	v_pk_add_f32 v[152:153], v[138:139], -1.0 op_sel_hi:[1,0]
	s_waitcnt lgkmcnt(2)
	v_pk_fma_f32 v[92:93], v[150:151], v[92:93], 1.0 op_sel_hi:[1,1,0]
	v_pk_fma_f32 v[90:91], v[152:153], v[90:91], 1.0 op_sel_hi:[1,1,0]
	v_pk_mul_f32 v[78:79], v[78:79], v[92:93]
	v_pk_mul_f32 v[74:75], v[74:75], v[90:91]
	v_pk_mul_f32 v[66:67], v[66:67], v[78:79]
	v_pk_mul_f32 v[70:71], v[70:71], v[74:75]
	s_waitcnt lgkmcnt(0)
	v_pk_mul_f32 v[66:67], v[148:149], v[66:67]
	v_pk_mul_f32 v[70:71], v[146:147], v[70:71]
	v_add_f32_e32 v66, v66, v67
	v_add_f32_e32 v70, v70, v71
	v_pk_mul_f32 v[82:83], v[82:83], v[160:161] op_sel_hi:[1,0]
	v_add_f32_e32 v66, v70, v66
	v_add_f32_e32 v129, v129, v66
	v_xor_b32_e32 v146, 0x80000000, v83
	v_xor_b32_e32 v147, 0x80000000, v82
	v_pk_mul_f32 v[70:71], v[140:141], v[82:83]
	v_pk_mul_f32 v[66:67], v[88:89], v[160:161] op_sel_hi:[1,0]
	v_pk_mul_f32 v[88:89], v[84:85], v[160:161] op_sel_hi:[1,0]
	ds_read_b128 v[82:85], v223 offset:43152
	v_pk_add_f32 v[90:91], v[136:137], -1.0 op_sel_hi:[1,0]
	v_pk_add_f32 v[92:93], v[134:135], -1.0 op_sel_hi:[1,0]
	v_pk_fma_f32 v[90:91], v[90:91], v[144:145], 1.0 op_sel_hi:[1,1,0]
	v_pk_fma_f32 v[92:93], v[92:93], v[142:143], 1.0 op_sel_hi:[1,1,0]
	v_pk_mul_f32 v[80:81], v[80:81], v[90:91]
	v_pk_mul_f32 v[76:77], v[76:77], v[92:93]
	v_pk_mul_f32 v[68:69], v[68:69], v[80:81]
	v_pk_mul_f32 v[72:73], v[72:73], v[76:77]
	s_waitcnt lgkmcnt(0)
	v_pk_mul_f32 v[68:69], v[84:85], v[68:69]
	v_pk_mul_f32 v[72:73], v[82:83], v[72:73]
	v_add_f32_e32 v68, v68, v69
	v_add_f32_e32 v72, v72, v73
	v_pk_mul_f32 v[86:87], v[86:87], v[160:161] op_sel_hi:[1,0]
	v_add_f32_e32 v68, v72, v68
	v_xor_b32_e32 v148, 0x80000000, v87
	v_xor_b32_e32 v149, 0x80000000, v86
	v_add_f32_e32 v90, v129, v68
	v_xor_b32_e32 v129, 0x80000000, v66
	v_pk_mul_f32 v[82:83], v[134:135], v[66:67]
	s_mov_b64 s[6:7], 0xc0
	v_cvt_pk_bf16_f32 v66, v74, v75
	v_pk_mul_f32 v[86:87], v[138:139], v[86:87]
	v_xor_b32_e32 v91, 0x80000000, v89
	v_xor_b32_e32 v92, 0x80000000, v88
	v_xor_b32_e32 v93, 0x80000000, v67
	v_lshl_add_u64 v[84:85], v[182:183], 0, s[6:7]
	v_cvt_pk_bf16_f32 v67, v78, v79
	v_cvt_pk_bf16_f32 v68, v76, v77
	v_cvt_pk_bf16_f32 v69, v80, v81
	global_store_dwordx4 v[84:85], v[66:69], off nt
	s_nop 1
	s_mov_b64 s[6:7], 0x140
	v_cvt_pk_bf16_f32 v66, v149, v148
	v_pk_mul_f32 v[72:73], v[136:137], v[88:89]
	v_lshl_add_u64 v[74:75], v[182:183], 0, s[6:7]
	v_cvt_pk_bf16_f32 v67, v147, v146
	v_cvt_pk_bf16_f32 v68, v129, v93
	v_cvt_pk_bf16_f32 v69, v92, v91
	global_store_dwordx4 v[74:75], v[66:69], off nt
	s_nop 1
	s_mov_b64 s[6:7], 0x1c0
	v_cvt_pk_bf16_f32 v66, v86, v87
	v_lshl_add_u64 v[74:75], v[182:183], 0, s[6:7]
	v_cvt_pk_bf16_f32 v67, v70, v71
	v_cvt_pk_bf16_f32 v68, v82, v83
	v_cvt_pk_bf16_f32 v69, v72, v73
	global_store_dwordx4 v[74:75], v[66:69], off nt
	s_nop 1
	ds_bpermute_b32 v66, v131, v90
	s_waitcnt lgkmcnt(0)
	v_add_f32_e32 v66, v90, v66
	v_mov_b32_e32 v67, v66
	s_nop 1
	v_permlane32_swap_b32_e32 v66, v67
	s_and_saveexec_b64 s[46:47], s[44:45]
	s_cbranch_execz .LBB0_912
	v_add_f32_e32 v68, v66, v67
	v_lshlrev_b64 v[66:67], 5, v[132:133]
	v_lshl_add_u64 v[66:67], s[58:59], 0, v[66:67]
	global_store_dword v[66:67], v68, off
.LBB0_912:
	s_or_b64 exec, exec, s[46:47]
	ds_read_b128 v[70:73], v224 offset:8448
	v_add_u32_e32 v66, 16, v132
	v_ashrrev_i32_e32 v67, 31, v66
	s_mov_b64 s[6:7], 0x7800400
	v_or_b32_e32 v68, 16, v128
	s_waitcnt lgkmcnt(0)
	v_mfma_f32_16x16x32_bf16 v[44:47], v[44:47], v[70:73], 0
	v_ashrrev_i32_e32 v69, 31, v68
	v_cmp_lt_i32_e32 vcc, -1, v227
	v_mfma_f32_16x16x32_bf16 v[50:53], v[50:53], v[70:73], 0
	s_nop 0
	v_cndmask_b32_e32 v128, 0, v210, vcc
	v_mfma_f32_16x16x32_bf16 v[54:57], v[54:57], v[70:73], 0
	v_mfma_f32_16x16x32_bf16 v[58:61], v[58:61], v[70:73], 0
	ds_read_b128 v[70:73], v224 offset:8512
	s_waitcnt lgkmcnt(0)
	v_mfma_f32_16x16x32_bf16 v[32:35], v[32:35], v[70:73], v[44:47]
	v_mfma_f32_16x16x32_bf16 v[36:39], v[36:39], v[70:73], v[50:53]
	v_mfma_f32_16x16x32_bf16 v[50:53], v[62:65], v[70:73], v[58:61]
	s_nop 0
	ds_read_b128 v[44:47], v222 offset:45056
	s_nop 0
	ds_read_b128 v[58:61], v222 offset:45072
	s_waitcnt lgkmcnt(1)
	s_nop 0
	v_add_f32_e32 v32, v32, v44
	v_add_f32_e32 v33, v33, v45
	v_mul_f32_e32 v32, 0xbfb8aa3b, v32
	v_mul_f32_e32 v33, 0xbfb8aa3b, v33
	v_exp_f32_e32 v32, v32
	v_exp_f32_e32 v33, v33
	v_mfma_f32_16x16x32_bf16 v[40:43], v[40:43], v[70:73], v[54:57]
	v_cndmask_b32_e64 v72, 0, 1.0, vcc
	v_add_f32_e32 v32, 1.0, v32
	v_add_f32_e32 v33, 1.0, v33
	v_rcp_f32_e32 v32, v32
	v_rcp_f32_e32 v33, v33
	s_nop 0
	v_pk_mul_f32 v[54:55], v[32:33], s[72:73] op_sel_hi:[1,0]
	v_add_f32_e32 v32, v34, v46
	v_add_f32_e32 v33, v35, v47
	v_mul_f32_e32 v32, 0xbfb8aa3b, v32
	v_mul_f32_e32 v33, 0xbfb8aa3b, v33
	v_exp_f32_e32 v32, v32
	v_exp_f32_e32 v33, v33
	v_add_f32_e32 v32, 1.0, v32
	v_add_f32_e32 v33, 1.0, v33
	v_rcp_f32_e32 v32, v32
	v_rcp_f32_e32 v33, v33
	s_nop 0
	v_pk_mul_f32 v[56:57], v[32:33], s[72:73] op_sel_hi:[1,0]
	s_waitcnt lgkmcnt(0)
	v_add_f32_e32 v32, v36, v58
	v_add_f32_e32 v33, v37, v59
	v_mul_f32_e32 v32, 0xbfb8aa3b, v32
	v_mul_f32_e32 v33, 0xbfb8aa3b, v33
	v_exp_f32_e32 v32, v32
	v_exp_f32_e32 v33, v33
	v_add_f32_e32 v32, 1.0, v32
	v_add_f32_e32 v33, 1.0, v33
	v_rcp_f32_e32 v32, v32
	v_rcp_f32_e32 v33, v33
	s_nop 0
	v_pk_mul_f32 v[58:59], v[32:33], s[72:73] op_sel_hi:[1,0]
	v_add_f32_e32 v32, v38, v60
	v_add_f32_e32 v33, v39, v61
	v_mul_f32_e32 v32, 0xbfb8aa3b, v32
	v_mul_f32_e32 v33, 0xbfb8aa3b, v33
	v_exp_f32_e32 v32, v32
	v_exp_f32_e32 v33, v33
	v_add_f32_e32 v32, 1.0, v32
	v_add_f32_e32 v33, 1.0, v33
	v_rcp_f32_e32 v32, v32
	v_rcp_f32_e32 v33, v33
	s_nop 0
	v_pk_mul_f32 v[60:61], v[32:33], s[72:73] op_sel_hi:[1,0]
	ds_read_b128 v[32:35], v222 offset:45184
	s_waitcnt lgkmcnt(0)
	v_add_f32_e32 v32, v40, v32
	v_add_f32_e32 v33, v41, v33
	v_mul_f32_e32 v32, 0xbfb8aa3b, v32
	v_mul_f32_e32 v33, 0xbfb8aa3b, v33
	v_exp_f32_e32 v32, v32
	v_exp_f32_e32 v33, v33
	v_add_f32_e32 v32, 1.0, v32
	v_add_f32_e32 v33, 1.0, v33
	v_rcp_f32_e32 v32, v32
	v_rcp_f32_e32 v33, v33
	s_nop 0
	v_pk_mul_f32 v[44:45], v[32:33], s[72:73] op_sel_hi:[1,0]
	v_add_f32_e32 v32, v42, v34
	v_add_f32_e32 v33, v43, v35
	v_mul_f32_e32 v32, 0xbfb8aa3b, v32
	v_mul_f32_e32 v33, 0xbfb8aa3b, v33
	v_exp_f32_e32 v32, v32
	v_exp_f32_e32 v33, v33
	v_add_f32_e32 v32, 1.0, v32
	v_add_f32_e32 v33, 1.0, v33
	v_rcp_f32_e32 v32, v32
	v_rcp_f32_e32 v33, v33
	s_nop 0
	v_pk_mul_f32 v[46:47], v[32:33], s[72:73] op_sel_hi:[1,0]
	ds_read_b128 v[32:35], v222 offset:45200
	s_waitcnt lgkmcnt(0)
	v_add_f32_e32 v32, v50, v32
	v_add_f32_e32 v33, v51, v33
	v_mul_f32_e32 v32, 0xbfb8aa3b, v32
	v_mul_f32_e32 v33, 0xbfb8aa3b, v33
	v_exp_f32_e32 v32, v32
	v_exp_f32_e32 v33, v33
	v_add_f32_e32 v32, 1.0, v32
	v_add_f32_e32 v33, 1.0, v33
	v_rcp_f32_e32 v32, v32
	v_rcp_f32_e32 v33, v33
	s_nop 0
	v_pk_mul_f32 v[50:51], v[32:33], s[72:73] op_sel_hi:[1,0]
	v_add_f32_e32 v32, v52, v34
	v_add_f32_e32 v33, v53, v35
	v_mul_f32_e32 v32, 0xbfb8aa3b, v32
	v_mul_f32_e32 v33, 0xbfb8aa3b, v33
	v_exp_f32_e32 v32, v32
	v_exp_f32_e32 v33, v33
	v_add_f32_e32 v32, 1.0, v32
	v_add_f32_e32 v33, 1.0, v33
	v_rcp_f32_e32 v32, v32
	v_rcp_f32_e32 v33, v33
	s_nop 0
	v_pk_mul_f32 v[52:53], v[32:33], s[72:73] op_sel_hi:[1,0]
	ds_read_b128 v[32:35], v224 offset:8576
	s_waitcnt lgkmcnt(0)
	v_mfma_f32_16x16x32_bf16 v[0:3], v[0:3], v[32:35], 0
	v_mfma_f32_16x16x32_bf16 v[4:7], v[4:7], v[32:35], 0
	v_mfma_f32_16x16x32_bf16 v[8:11], v[8:11], v[32:35], 0
	v_mfma_f32_16x16x32_bf16 v[12:15], v[12:15], v[32:35], 0
	ds_read_b128 v[32:35], v224 offset:8640
	s_waitcnt lgkmcnt(0)
	v_mfma_f32_16x16x32_bf16 v[0:3], v[16:19], v[32:35], v[0:3]
	ds_read_b128 v[16:19], v222 offset:47104
	v_mfma_f32_16x16x32_bf16 v[4:7], v[20:23], v[32:35], v[4:7]
	global_load_dwordx4 v[20:23], v[112:113], off offset:64
	s_waitcnt lgkmcnt(0)
	s_nop 3
	v_add_f32_e32 v0, v0, v16
	v_mul_f32_e32 v0, 0xbfb8aa3b, v0
	v_exp_f32_e32 v0, v0
	v_mfma_f32_16x16x32_bf16 v[8:11], v[24:27], v[32:35], v[8:11]
	v_add_f32_e32 v0, 1.0, v0
	v_rcp_f32_e32 v40, v0
	v_add_f32_e32 v0, v1, v17
	v_mul_f32_e32 v0, 0xbfb8aa3b, v0
	v_exp_f32_e32 v0, v0
	v_mfma_f32_16x16x32_bf16 v[12:15], v[28:31], v[32:35], v[12:15]
	v_add_f32_e32 v0, 1.0, v0
	v_rcp_f32_e32 v41, v0
	v_add_f32_e32 v0, v2, v18
	v_mul_f32_e32 v0, 0xbfb8aa3b, v0
	v_exp_f32_e32 v0, v0
	s_nop 0
	v_add_f32_e32 v0, 1.0, v0
	v_rcp_f32_e32 v42, v0
	v_add_f32_e32 v0, v3, v19
	v_mul_f32_e32 v0, 0xbfb8aa3b, v0
	v_exp_f32_e32 v0, v0
	global_load_dwordx4 v[16:19], v[118:119], off
	v_add_f32_e32 v0, 1.0, v0
	v_rcp_f32_e32 v43, v0
	ds_read_b128 v[0:3], v222 offset:47120
	s_waitcnt lgkmcnt(0)
	v_add_f32_e32 v0, v4, v0
	v_mul_f32_e32 v0, 0xbfb8aa3b, v0
	v_exp_f32_e32 v0, v0
	s_nop 0
	v_add_f32_e32 v0, 1.0, v0
	v_rcp_f32_e32 v36, v0
	v_add_f32_e32 v0, v5, v1
	v_mul_f32_e32 v0, 0xbfb8aa3b, v0
	v_exp_f32_e32 v0, v0
	s_nop 0
	v_add_f32_e32 v0, 1.0, v0
	v_rcp_f32_e32 v37, v0
	v_add_f32_e32 v0, v6, v2
	v_mul_f32_e32 v0, 0xbfb8aa3b, v0
	v_exp_f32_e32 v0, v0
	s_nop 0
	v_add_f32_e32 v0, 1.0, v0
	v_rcp_f32_e32 v38, v0
	v_add_f32_e32 v0, v7, v3
	v_mul_f32_e32 v0, 0xbfb8aa3b, v0
	v_exp_f32_e32 v0, v0
	global_load_dwordx4 v[4:7], v[112:113], off
	v_add_f32_e32 v0, 1.0, v0
	v_rcp_f32_e32 v39, v0
	ds_read_b128 v[0:3], v222 offset:47232
	s_waitcnt lgkmcnt(0)
	v_add_f32_e32 v0, v8, v0
	v_mul_f32_e32 v0, 0xbfb8aa3b, v0
	v_exp_f32_e32 v0, v0
	s_nop 0
	v_add_f32_e32 v0, 1.0, v0
	v_rcp_f32_e32 v32, v0
	v_add_f32_e32 v0, v9, v1
	v_mul_f32_e32 v0, 0xbfb8aa3b, v0
	v_exp_f32_e32 v0, v0
	s_nop 0
	v_add_f32_e32 v0, 1.0, v0
	v_rcp_f32_e32 v33, v0
	v_add_f32_e32 v0, v10, v2
	v_mul_f32_e32 v0, 0xbfb8aa3b, v0
	v_exp_f32_e32 v0, v0
	s_nop 0
	v_add_f32_e32 v0, 1.0, v0
	v_rcp_f32_e32 v34, v0
	v_add_f32_e32 v0, v11, v3
	v_mul_f32_e32 v0, 0xbfb8aa3b, v0
	v_exp_f32_e32 v0, v0
	global_load_dwordx4 v[8:11], v[114:115], off
	global_load_dwordx4 v[242:245], v[114:115], off offset:64
	global_load_dwordx4 v[246:249], v[116:117], off offset:64
	global_load_dwordx4 v[250:253], v[118:119], off offset:64
	v_add_f32_e32 v0, 1.0, v0
	v_rcp_f32_e32 v35, v0
	ds_read_b128 v[0:3], v222 offset:47248
	s_waitcnt lgkmcnt(0)
	v_add_f32_e32 v0, v12, v0
	v_mul_f32_e32 v0, 0xbfb8aa3b, v0
	v_exp_f32_e32 v0, v0
	s_nop 0
	v_add_f32_e32 v0, 1.0, v0
	v_rcp_f32_e32 v28, v0
	v_add_f32_e32 v0, v13, v1
	v_mul_f32_e32 v0, 0xbfb8aa3b, v0
	v_exp_f32_e32 v0, v0
	s_nop 0
	v_add_f32_e32 v0, 1.0, v0
	v_rcp_f32_e32 v29, v0
	v_add_f32_e32 v0, v14, v2
	v_mul_f32_e32 v0, 0xbfb8aa3b, v0
	v_exp_f32_e32 v0, v0
	s_nop 0
	v_add_f32_e32 v0, 1.0, v0
	v_rcp_f32_e32 v30, v0
	v_add_f32_e32 v0, v15, v3
	global_load_dwordx4 v[12:15], v[116:117], off
	v_mul_f32_e32 v0, 0xbfb8aa3b, v0
	v_exp_f32_e32 v0, v0
	s_nop 0
	v_add_f32_e32 v0, 1.0, v0
	v_rcp_f32_e32 v31, v0
	ds_read_b128 v[0:3], v224 offset:8704
	s_waitcnt vmcnt(5) lgkmcnt(0)
	v_mfma_f32_16x16x32_bf16 v[4:7], v[4:7], v[0:3], 0
	s_waitcnt vmcnt(4)
	v_mfma_f32_16x16x32_bf16 v[8:11], v[8:11], v[0:3], 0
	s_waitcnt vmcnt(0)
	v_mfma_f32_16x16x32_bf16 v[12:15], v[12:15], v[0:3], 0
	v_mfma_f32_16x16x32_bf16 v[0:3], v[16:19], v[0:3], 0
	ds_read_b128 v[16:19], v224 offset:8768
	s_waitcnt lgkmcnt(0)
	v_mfma_f32_16x16x32_bf16 v[4:7], v[20:23], v[16:19], v[4:7]
	global_load_dwordx4 v[20:23], v[112:113], off offset:128
	v_mfma_f32_16x16x32_bf16 v[8:11], v[242:245], v[16:19], v[8:11]
	global_load_dwordx4 v[242:245], v[114:115], off offset:128
	v_mfma_f32_16x16x32_bf16 v[12:15], v[246:249], v[16:19], v[12:15]
	global_load_dwordx4 v[246:249], v[116:117], off offset:128
	v_mfma_f32_16x16x32_bf16 v[0:3], v[250:253], v[16:19], v[0:3]
	global_load_dwordx4 v[250:253], v[118:119], off offset:128
	ds_read_b128 v[16:19], v224 offset:8832
	s_waitcnt vmcnt(3) lgkmcnt(0)
	v_mfma_f32_16x16x32_bf16 v[20:23], v[20:23], v[16:19], v[4:7]
	s_waitcnt vmcnt(2)
	v_mfma_f32_16x16x32_bf16 v[24:27], v[242:245], v[16:19], v[8:11]
	s_nop 2
	global_load_dwordx4 v[8:11], v[112:113], off offset:192
	global_load_dwordx4 v[242:245], v[116:117], off offset:192
	s_waitcnt vmcnt(3)
	v_mfma_f32_16x16x32_bf16 v[62:65], v[246:249], v[16:19], v[12:15]
	s_nop 2
	global_load_dwordx4 v[12:15], v[114:115], off offset:192
	global_load_dwordx4 v[246:249], v[118:119], off offset:192
	s_waitcnt vmcnt(4)
	v_mfma_f32_16x16x32_bf16 v[0:3], v[250:253], v[16:19], v[0:3]
	ds_read_b128 v[4:7], v224 offset:8896
	s_waitcnt vmcnt(3) lgkmcnt(0)
	v_mfma_f32_16x16x32_bf16 v[8:11], v[8:11], v[4:7], v[20:23]
	s_waitcnt vmcnt(1)
	v_mfma_f32_16x16x32_bf16 v[12:15], v[12:15], v[4:7], v[24:27]
	v_mfma_f32_16x16x32_bf16 v[16:19], v[242:245], v[4:7], v[62:65]
	s_waitcnt vmcnt(0)
	v_mfma_f32_16x16x32_bf16 v[0:3], v[246:249], v[4:7], v[0:3]
	v_lshlrev_b64 v[4:5], 11, v[66:67]
	v_lshl_add_u64 v[4:5], s[2:3], 0, v[4:5]
	v_lshl_add_u64 v[4:5], s[56:57], 1, v[4:5]
	v_lshl_add_u64 v[20:21], v[4:5], 0, v[48:49]
	v_lshl_add_u64 v[22:23], v[20:21], 0, s[6:7]
	v_cvt_pk_bf16_f32 v6, v12, v13
	s_mov_b64 s[6:7], 0x7800440
	v_cvt_pk_bf16_f32 v4, v8, v9
	v_cvt_pk_bf16_f32 v5, v10, v11
	v_cvt_pk_bf16_f32 v7, v14, v15
	global_store_dwordx4 v[22:23], v[4:7], off nt
	s_nop 1
	v_cvt_pk_bf16_f32 v6, v0, v1
	v_lshl_add_u64 v[0:1], v[20:21], 0, s[6:7]
	v_cvt_pk_bf16_f32 v4, v16, v17
	v_cvt_pk_bf16_f32 v5, v18, v19
	v_cvt_pk_bf16_f32 v7, v2, v3
	global_store_dwordx4 v[0:1], v[4:7], off nt
	s_nop 1
	v_lshl_add_u64 v[0:1], v[126:127], 0, v[68:69]
	v_mov_b64_e32 v[2:3], s[54:55]
	v_mad_u64_u32 v[78:79], s[6:7], v0, s95, v[2:3]
	v_mad_i32_i24 v79, v1, s95, v79
	v_mov_b64_e32 v[0:1], s[12:13]
	v_mad_i64_i32 v[132:133], s[6:7], v66, s19, v[0:1]
	v_ashrrev_i32_e32 v0, 31, v227
	v_not_b32_e32 v129, v0
	v_lshl_add_u64 v[12:13], v[120:121], 1, v[132:133]
	s_mov_b64 s[6:7], 0x800
	v_lshl_add_u64 v[8:9], v[12:13], 0, s[6:7]
	v_lshl_add_u64 v[16:17], v[12:13], 0, v[128:129]
	global_load_dwordx4 v[4:7], v[12:13], off offset:2048
	global_load_dwordx4 v[0:3], v[12:13], off offset:3072
	s_nop 0
	global_load_dwordx4 v[8:11], v[8:9], off offset:2048
	v_lshl_add_u64 v[20:21], v[16:17], 0, s[6:7]
	global_load_dwordx4 v[12:15], v[16:17], off offset:2048
	s_nop 0
	global_load_dwordx4 v[16:19], v[16:17], off offset:3072
	s_nop 0
	global_load_dwordx4 v[20:23], v[20:21], off offset:2048
	ds_read_b128 v[68:71], v223 offset:32768
	ds_read_b128 v[24:27], v223 offset:32784
	ds_read_b128 v[74:77], v223 offset:34816
	ds_read_b128 v[80:83], v223 offset:36864
	v_lshl_add_u64 v[78:79], v[78:79], 0, v[48:49]
	s_mov_b64 s[6:7], 0x280
	s_waitcnt vmcnt(5)
	v_lshlrev_b32_e32 v64, 16, v4
	v_and_b32_e32 v65, 0xffff0000, v4
	v_lshlrev_b32_e32 v4, 16, v5
	v_and_b32_e32 v5, 0xffff0000, v5
	s_waitcnt vmcnt(2)
	v_lshlrev_b32_e32 v62, 16, v12
	v_and_b32_e32 v63, 0xffff0000, v12
	v_xor_b32_e32 v93, 0x80000000, v65
	v_xor_b32_e32 v92, 0x80000000, v64
	v_lshlrev_b32_e32 v12, 16, v13
	v_and_b32_e32 v13, 0xffff0000, v13
	v_pk_fma_f32 v[92:93], v[72:73], v[62:63], v[92:93] op_sel_hi:[0,1,1]
	v_xor_b32_e32 v63, 0x80000000, v5
	v_xor_b32_e32 v62, 0x80000000, v4
	v_lshlrev_b32_e32 v84, 16, v0
	v_and_b32_e32 v85, 0xffff0000, v0
	v_lshlrev_b32_e32 v0, 16, v1
	v_and_b32_e32 v1, 0xffff0000, v1
	v_pk_fma_f32 v[12:13], v[72:73], v[12:13], v[62:63] op_sel_hi:[0,1,1]
	s_waitcnt vmcnt(1)
	v_lshlrev_b32_e32 v88, 16, v16
	v_and_b32_e32 v89, 0xffff0000, v16
	v_lshlrev_b32_e32 v16, 16, v17
	v_and_b32_e32 v17, 0xffff0000, v17
	s_waitcnt lgkmcnt(3)
	v_pk_fma_f32 v[62:63], v[70:71], v[12:13], v[4:5]
	v_xor_b32_e32 v5, 0x80000000, v85
	v_xor_b32_e32 v4, 0x80000000, v84
	v_xor_b32_e32 v13, 0x80000000, v1
	v_xor_b32_e32 v12, 0x80000000, v0
	v_pk_fma_f32 v[4:5], v[72:73], v[88:89], v[4:5] op_sel_hi:[0,1,1]
	v_pk_fma_f32 v[12:13], v[72:73], v[16:17], v[12:13] op_sel_hi:[0,1,1]
	v_pk_fma_f32 v[64:65], v[68:69], v[92:93], v[64:65]
	s_waitcnt lgkmcnt(1)
	v_pk_fma_f32 v[68:69], v[76:77], v[12:13], v[0:1]
	v_pk_fma_f32 v[70:71], v[74:75], v[4:5], v[84:85]
	ds_read_b128 v[74:77], v223 offset:38912
	v_lshlrev_b32_e32 v86, 16, v8
	v_and_b32_e32 v87, 0xffff0000, v8
	v_lshlrev_b32_e32 v8, 16, v9
	v_and_b32_e32 v9, 0xffff0000, v9
	s_waitcnt vmcnt(0)
	v_lshlrev_b32_e32 v90, 16, v20
	v_and_b32_e32 v91, 0xffff0000, v20
	v_xor_b32_e32 v1, 0x80000000, v87
	v_xor_b32_e32 v0, 0x80000000, v86
	v_lshlrev_b32_e32 v20, 16, v21
	v_and_b32_e32 v21, 0xffff0000, v21
	v_pk_fma_f32 v[4:5], v[72:73], v[90:91], v[0:1] op_sel_hi:[0,1,1]
	v_xor_b32_e32 v1, 0x80000000, v9
	v_xor_b32_e32 v0, 0x80000000, v8
	v_pk_fma_f32 v[0:1], v[72:73], v[20:21], v[0:1] op_sel_hi:[0,1,1]
	s_waitcnt lgkmcnt(0)
	v_pk_mul_f32 v[74:75], v[74:75], v[70:71]
	v_pk_mul_f32 v[76:77], v[76:77], v[68:69]
	v_pk_fma_f32 v[0:1], v[82:83], v[0:1], v[8:9]
	v_pk_mul_f32 v[8:9], v[76:77], v[76:77]
	v_pk_mul_f32 v[12:13], v[74:75], v[74:75]
	v_lshlrev_b32_e32 v20, 16, v6
	v_pk_mov_b32 v[16:17], v[12:13], v[8:9] op_sel:[1,0]
	v_mov_b32_e32 v13, v9
	v_pk_add_f32 v[8:9], v[16:17], v[12:13]
	v_and_b32_e32 v21, 0xffff0000, v6
	v_pk_fma_f32 v[4:5], v[80:81], v[4:5], v[86:87]
	v_pk_add_f32 v[88:89], v[8:9], v[8:9] op_sel_hi:[0,1]
	v_lshlrev_b32_e32 v80, 16, v7
	v_and_b32_e32 v81, 0xffff0000, v7
	v_lshlrev_b32_e32 v86, 16, v2
	v_and_b32_e32 v87, 0xffff0000, v2
	v_lshlrev_b32_e32 v84, 16, v3
	v_and_b32_e32 v85, 0xffff0000, v3
	v_lshlrev_b32_e32 v2, 16, v10
	v_and_b32_e32 v3, 0xffff0000, v10
	v_lshlrev_b32_e32 v6, 16, v11
	v_and_b32_e32 v7, 0xffff0000, v11
	v_lshlrev_b32_e32 v82, 16, v14
	v_and_b32_e32 v83, 0xffff0000, v14
	v_lshlrev_b32_e32 v10, 16, v22
	v_and_b32_e32 v11, 0xffff0000, v22
	v_lshlrev_b32_e32 v8, 16, v23
	v_and_b32_e32 v9, 0xffff0000, v23
	v_xor_b32_e32 v23, 0x80000000, v21
	v_xor_b32_e32 v22, 0x80000000, v20
	v_lshlrev_b32_e32 v90, 16, v15
	v_and_b32_e32 v91, 0xffff0000, v15
	v_lshlrev_b32_e32 v92, 16, v18
	v_and_b32_e32 v93, 0xffff0000, v18
	v_lshlrev_b32_e32 v126, 16, v19
	v_and_b32_e32 v127, 0xffff0000, v19
	ds_read_b128 v[12:15], v223 offset:34832
	ds_read_b128 v[16:19], v223 offset:36880
	v_pk_fma_f32 v[22:23], v[72:73], v[82:83], v[22:23] op_sel_hi:[0,1,1]
	v_xor_b32_e32 v83, 0x80000000, v81
	v_xor_b32_e32 v82, 0x80000000, v80
	v_pk_fma_f32 v[82:83], v[72:73], v[90:91], v[82:83] op_sel_hi:[0,1,1]
	v_pk_fma_f32 v[80:81], v[26:27], v[82:83], v[80:81]
	v_pk_fma_f32 v[82:83], v[24:25], v[22:23], v[20:21]
	v_xor_b32_e32 v21, 0x80000000, v87
	v_xor_b32_e32 v20, 0x80000000, v86
	v_pk_fma_f32 v[20:21], v[72:73], v[92:93], v[20:21] op_sel_hi:[0,1,1]
	s_waitcnt lgkmcnt(1)
	v_pk_fma_f32 v[86:87], v[12:13], v[20:21], v[86:87]
	v_xor_b32_e32 v13, 0x80000000, v3
	v_xor_b32_e32 v12, 0x80000000, v2
	v_pk_fma_f32 v[10:11], v[72:73], v[10:11], v[12:13] op_sel_hi:[0,1,1]
	v_xor_b32_e32 v13, 0x80000000, v7
	v_xor_b32_e32 v12, 0x80000000, v6
	v_pk_fma_f32 v[8:9], v[72:73], v[8:9], v[12:13] op_sel_hi:[0,1,1]
	s_waitcnt lgkmcnt(0)
	v_pk_fma_f32 v[12:13], v[18:19], v[8:9], v[6:7]
	ds_read_b128 v[6:9], v223 offset:38928
	v_xor_b32_e32 v23, 0x80000000, v85
	v_xor_b32_e32 v22, 0x80000000, v84
	v_pk_fma_f32 v[22:23], v[72:73], v[126:127], v[22:23] op_sel_hi:[0,1,1]
	v_pk_fma_f32 v[84:85], v[14:15], v[22:23], v[84:85]
	s_waitcnt lgkmcnt(0)
	v_pk_mul_f32 v[90:91], v[6:7], v[86:87]
	v_pk_mul_f32 v[92:93], v[8:9], v[84:85]
	v_pk_fma_f32 v[10:11], v[16:17], v[10:11], v[2:3]
	v_pk_mul_f32 v[2:3], v[92:93], v[92:93]
	v_pk_mul_f32 v[6:7], v[90:91], v[90:91]
	s_nop 0
	v_pk_mov_b32 v[8:9], v[6:7], v[2:3] op_sel:[1,0]
	v_mov_b32_e32 v7, v3
	v_pk_add_f32 v[2:3], v[8:9], v[6:7]
	v_lshl_add_u64 v[6:7], v[78:79], 0, s[6:7]
	v_pk_add_f32 v[126:127], v[2:3], v[2:3] op_sel_hi:[0,1]
	v_cvt_pk_bf16_f32 v2, v4, v5
	v_cvt_pk_bf16_f32 v3, v0, v1
	v_cvt_pk_bf16_f32 v4, v10, v11
	v_cvt_pk_bf16_f32 v5, v12, v13
	global_store_dwordx4 v[6:7], v[2:5], off nt
	s_nop 1
	s_mov_b64 s[6:7], 0x200
	v_lshl_add_u64 v[4:5], v[78:79], 0, s[6:7]
	v_cvt_pk_bf16_f32 v0, v64, v65
	v_cvt_pk_bf16_f32 v1, v62, v63
	v_cvt_pk_bf16_f32 v2, v82, v83
	v_cvt_pk_bf16_f32 v3, v80, v81
	global_store_dwordx4 v[4:5], v[0:3], off nt
	s_nop 1
	v_lshl_add_u64 v[12:13], v[122:123], 1, v[132:133]
	s_mov_b64 s[6:7], 0x840
	v_cvt_pk_bf16_f32 v0, v54, v55
	v_cvt_pk_bf16_f32 v1, v56, v57
	v_cvt_pk_bf16_f32 v2, v58, v59
	v_cvt_pk_bf16_f32 v3, v60, v61
	global_store_dwordx4 v[78:79], v[0:3], off nt
	s_nop 1
	v_lshl_add_u64 v[8:9], v[12:13], 0, s[6:7]
	v_lshl_add_u64 v[16:17], v[12:13], 0, v[128:129]
	global_load_dwordx4 v[0:3], v[12:13], off offset:2112
	global_load_dwordx4 v[4:7], v[12:13], off offset:3136
	s_nop 0
	global_load_dwordx4 v[8:11], v[8:9], off offset:2048
	v_lshl_add_u64 v[20:21], v[16:17], 0, s[6:7]
	global_load_dwordx4 v[12:15], v[16:17], off offset:2112
	s_nop 0
	global_load_dwordx4 v[16:19], v[16:17], off offset:3136
	s_nop 0
	global_load_dwordx4 v[20:23], v[20:21], off offset:2048
	ds_read_b128 v[54:57], v223 offset:32896
	ds_read_b128 v[24:27], v223 offset:32912
	ds_read_b128 v[58:61], v223 offset:34944
	ds_read_b128 v[132:135], v223 offset:36992
	s_mov_b64 s[6:7], 0x2c0
	s_waitcnt vmcnt(5)
	v_lshlrev_b32_e32 v128, 16, v0
	v_and_b32_e32 v129, 0xffff0000, v0
	v_lshlrev_b32_e32 v0, 16, v1
	v_and_b32_e32 v1, 0xffff0000, v1
	s_waitcnt vmcnt(4)
	v_lshlrev_b32_e32 v136, 16, v4
	v_and_b32_e32 v137, 0xffff0000, v4
	v_lshlrev_b32_e32 v138, 16, v5
	v_and_b32_e32 v139, 0xffff0000, v5
	s_waitcnt vmcnt(2)
	v_lshlrev_b32_e32 v4, 16, v12
	v_and_b32_e32 v5, 0xffff0000, v12
	v_xor_b32_e32 v147, 0x80000000, v129
	v_xor_b32_e32 v146, 0x80000000, v128
	v_lshlrev_b32_e32 v140, 16, v8
	v_and_b32_e32 v141, 0xffff0000, v8
	v_lshlrev_b32_e32 v142, 16, v9
	v_and_b32_e32 v143, 0xffff0000, v9
	v_lshlrev_b32_e32 v8, 16, v13
	v_and_b32_e32 v9, 0xffff0000, v13
	v_pk_fma_f32 v[4:5], v[72:73], v[4:5], v[146:147] op_sel_hi:[0,1,1]
	v_xor_b32_e32 v147, 0x80000000, v1
	v_xor_b32_e32 v146, 0x80000000, v0
	v_pk_fma_f32 v[8:9], v[72:73], v[8:9], v[146:147] op_sel_hi:[0,1,1]
	s_waitcnt vmcnt(1)
	v_lshlrev_b32_e32 v12, 16, v16
	v_and_b32_e32 v13, 0xffff0000, v16
	v_lshlrev_b32_e32 v16, 16, v17
	v_and_b32_e32 v17, 0xffff0000, v17
	s_waitcnt lgkmcnt(3)
	v_pk_fma_f32 v[0:1], v[56:57], v[8:9], v[0:1]
	v_xor_b32_e32 v9, 0x80000000, v139
	v_xor_b32_e32 v8, 0x80000000, v138
	v_pk_fma_f32 v[16:17], v[72:73], v[16:17], v[8:9] op_sel_hi:[0,1,1]
	v_xor_b32_e32 v9, 0x80000000, v137
	v_xor_b32_e32 v8, 0x80000000, v136
	s_waitcnt vmcnt(0)
	v_lshlrev_b32_e32 v144, 16, v20
	v_and_b32_e32 v145, 0xffff0000, v20
	v_lshlrev_b32_e32 v20, 16, v21
	v_and_b32_e32 v21, 0xffff0000, v21
	v_pk_fma_f32 v[4:5], v[54:55], v[4:5], v[128:129]
	v_pk_fma_f32 v[8:9], v[72:73], v[12:13], v[8:9] op_sel_hi:[0,1,1]
	s_waitcnt lgkmcnt(1)
	v_pk_fma_f32 v[12:13], v[60:61], v[16:17], v[138:139]
	v_xor_b32_e32 v17, 0x80000000, v141
	v_xor_b32_e32 v16, 0x80000000, v140
	v_xor_b32_e32 v55, 0x80000000, v143
	v_xor_b32_e32 v54, 0x80000000, v142
	v_pk_fma_f32 v[16:17], v[72:73], v[144:145], v[16:17] op_sel_hi:[0,1,1]
	v_pk_fma_f32 v[20:21], v[72:73], v[20:21], v[54:55] op_sel_hi:[0,1,1]
	v_lshlrev_b32_e32 v128, 16, v2
	v_and_b32_e32 v129, 0xffff0000, v2
	s_waitcnt lgkmcnt(0)
	v_pk_fma_f32 v[54:55], v[134:135], v[20:21], v[142:143]
	v_pk_fma_f32 v[56:57], v[132:133], v[16:17], v[140:141]
	v_lshlrev_b32_e32 v2, 16, v3
	v_and_b32_e32 v3, 0xffff0000, v3
	v_lshlrev_b32_e32 v140, 16, v6
	v_and_b32_e32 v141, 0xffff0000, v6
	v_lshlrev_b32_e32 v142, 16, v7
	v_and_b32_e32 v143, 0xffff0000, v7
	v_lshlrev_b32_e32 v6, 16, v14
	v_and_b32_e32 v7, 0xffff0000, v14
	v_xor_b32_e32 v151, 0x80000000, v129
	v_xor_b32_e32 v150, 0x80000000, v128
	v_lshlrev_b32_e32 v144, 16, v10
	v_and_b32_e32 v145, 0xffff0000, v10
	v_lshlrev_b32_e32 v146, 16, v11
	v_and_b32_e32 v147, 0xffff0000, v11
	v_lshlrev_b32_e32 v10, 16, v15
	v_and_b32_e32 v11, 0xffff0000, v15
	v_pk_fma_f32 v[6:7], v[72:73], v[6:7], v[150:151] op_sel_hi:[0,1,1]
	v_xor_b32_e32 v151, 0x80000000, v3
	v_xor_b32_e32 v150, 0x80000000, v2
	v_pk_fma_f32 v[8:9], v[58:59], v[8:9], v[136:137]
	ds_read_b128 v[58:61], v223 offset:39040
	ds_read_b128 v[132:135], v223 offset:34960
	ds_read_b128 v[136:139], v223 offset:37008
	v_pk_fma_f32 v[10:11], v[72:73], v[10:11], v[150:151] op_sel_hi:[0,1,1]
	v_lshlrev_b32_e32 v14, 16, v18
	v_and_b32_e32 v15, 0xffff0000, v18
	v_lshlrev_b32_e32 v18, 16, v19
	v_and_b32_e32 v19, 0xffff0000, v19
	v_pk_fma_f32 v[2:3], v[26:27], v[10:11], v[2:3]
	v_xor_b32_e32 v11, 0x80000000, v143
	v_xor_b32_e32 v10, 0x80000000, v142
	v_pk_fma_f32 v[18:19], v[72:73], v[18:19], v[10:11] op_sel_hi:[0,1,1]
	v_xor_b32_e32 v11, 0x80000000, v141
	v_xor_b32_e32 v10, 0x80000000, v140
	v_pk_fma_f32 v[10:11], v[72:73], v[14:15], v[10:11] op_sel_hi:[0,1,1]
	s_waitcnt lgkmcnt(1)
	v_pk_fma_f32 v[10:11], v[132:133], v[10:11], v[140:141]
	v_pk_fma_f32 v[14:15], v[134:135], v[18:19], v[142:143]
	ds_read_b128 v[132:135], v223 offset:39056
	v_pk_mul_f32 v[20:21], v[58:59], v[8:9]
	v_pk_mul_f32 v[16:17], v[60:61], v[12:13]
	v_mul_f32_e32 v58, v20, v20
	v_pk_fma_f32 v[58:59], v[20:21], v[20:21], v[58:59] op_sel_hi:[1,1,0]
	v_lshlrev_b32_e32 v148, 16, v22
	v_and_b32_e32 v149, 0xffff0000, v22
	v_lshlrev_b32_e32 v22, 16, v23
	v_and_b32_e32 v23, 0xffff0000, v23
	v_pk_fma_f32 v[6:7], v[24:25], v[6:7], v[128:129]
	v_xor_b32_e32 v19, 0x80000000, v145
	v_xor_b32_e32 v18, 0x80000000, v144
	v_xor_b32_e32 v25, 0x80000000, v147
	v_xor_b32_e32 v24, 0x80000000, v146
	v_mul_f32_e32 v58, v16, v16
	v_pk_fma_f32 v[18:19], v[72:73], v[148:149], v[18:19] op_sel_hi:[0,1,1]
	v_pk_fma_f32 v[22:23], v[72:73], v[22:23], v[24:25] op_sel_hi:[0,1,1]
	v_pk_fma_f32 v[60:61], v[16:17], v[16:17], v[58:59] op_sel_hi:[1,1,0]
	s_waitcnt lgkmcnt(1)
	v_pk_fma_f32 v[24:25], v[138:139], v[22:23], v[146:147]
	v_pk_fma_f32 v[26:27], v[136:137], v[18:19], v[144:145]
	s_waitcnt lgkmcnt(0)
	v_pk_mul_f32 v[18:19], v[134:135], v[14:15]
	v_pk_mul_f32 v[22:23], v[132:133], v[10:11]
	v_mul_f32_e32 v58, v18, v18
	v_mul_f32_e32 v88, v22, v22
	v_mul_f32_e32 v126, v23, v23
	v_mul_f32_e32 v60, v19, v19
	v_pk_add_f32 v[72:73], v[88:89], v[126:127]
	v_pk_add_f32 v[58:59], v[58:59], v[60:61]
	v_lshl_add_u64 v[60:61], v[78:79], 0, s[6:7]
	v_pk_add_f32 v[58:59], v[72:73], v[58:59]
	v_cvt_pk_bf16_f32 v56, v56, v57
	v_add_f32_e32 v72, v58, v59
	v_cvt_pk_bf16_f32 v57, v54, v55
	v_cvt_pk_bf16_f32 v58, v26, v27
	v_cvt_pk_bf16_f32 v59, v24, v25
	global_store_dwordx4 v[60:61], v[56:59], off nt
	s_nop 1
	s_mov_b64 s[6:7], 0x240
	v_cvt_pk_bf16_f32 v24, v4, v5
	v_lshl_add_u64 v[54:55], v[78:79], 0, s[6:7]
	v_cvt_pk_bf16_f32 v25, v0, v1
	v_cvt_pk_bf16_f32 v26, v6, v7
	v_cvt_pk_bf16_f32 v27, v2, v3
	global_store_dwordx4 v[54:55], v[24:27], off nt
	s_nop 1
	v_cvt_pk_bf16_f32 v24, v44, v45
	v_lshl_add_u64 v[54:55], v[78:79], 0, 64
	v_cvt_pk_bf16_f32 v25, v46, v47
	v_cvt_pk_bf16_f32 v26, v50, v51
	v_cvt_pk_bf16_f32 v27, v52, v53
	global_store_dwordx4 v[54:55], v[24:27], off nt
	s_nop 1
	s_mov_b32 s6, 0xf800000
	v_pk_add_f32 v[60:61], v[42:43], -1.0 op_sel_hi:[1,0]
	s_waitcnt lgkmcnt(0)
	v_mov_b32_e32 v24, v72
	s_nop 1
	v_permlane16_swap_b32_e32 v72, v24
	v_add_f32_e32 v24, v72, v24
	v_mov_b32_e32 v25, v24
	s_nop 1
	v_permlane32_swap_b32_e32 v24, v25
	v_add_f32_e32 v24, v24, v25
	v_cmp_gt_f32_e32 vcc, s6, v24
	v_mul_f32_e32 v25, 0x4f800000, v24
	v_pk_add_f32 v[72:73], v[40:41], -1.0 op_sel_hi:[1,0]
	v_cndmask_b32_e32 v24, v24, v25, vcc
	v_sqrt_f32_e32 v25, v24
	s_nop 0
	v_add_u32_e32 v26, -1, v25
	v_fma_f32 v27, -v26, v25, v24
	v_cmp_ge_f32_e64 s[46:47], 0, v27
	v_add_u32_e32 v27, 1, v25
	s_nop 0
	v_cndmask_b32_e64 v26, v25, v26, s[46:47]
	v_fma_f32 v25, -v27, v25, v24
	v_cmp_lt_f32_e64 s[46:47], 0, v25
	s_nop 1
	v_cndmask_b32_e64 v25, v26, v27, s[46:47]
	v_mul_f32_e32 v26, 0x37800000, v25
	v_cndmask_b32_e32 v25, v25, v26, vcc
	v_cmp_class_f32_e32 vcc, v24, v207
	s_nop 1
	v_cndmask_b32_e32 v24, v25, v24, vcc
	v_max_f32_e32 v24, 0x2b8cbccc, v24
	v_div_scale_f32 v25, s[6:7], v24, v24, 1.0
	v_rcp_f32_e32 v26, v25
	s_mov_b64 s[6:7], 0x180
	v_fma_f32 v27, -v25, v26, 1.0
	v_fmac_f32_e32 v26, v27, v26
	v_div_scale_f32 v27, vcc, 1.0, v24, 1.0
	v_mul_f32_e32 v44, v27, v26
	v_fma_f32 v45, -v25, v44, v27
	v_fmac_f32_e32 v44, v45, v26
	v_fma_f32 v25, -v25, v44, v27
	v_div_fmas_f32 v25, v25, v26, v44
	v_div_fixup_f32 v54, v25, v24, 1.0
	ds_read_b128 v[24:27], v223 offset:40960
	ds_read_b128 v[44:47], v223 offset:40976
	ds_read_b128 v[50:53], v223 offset:43008
	v_pk_mul_f32 v[56:57], v[74:75], v[54:55] op_sel_hi:[1,0]
	v_pk_mul_f32 v[58:59], v[76:77], v[54:55] op_sel_hi:[1,0]
	s_waitcnt lgkmcnt(2)
	v_pk_fma_f32 v[24:25], v[72:73], v[24:25], 1.0 op_sel_hi:[1,1,0]
	v_pk_fma_f32 v[26:27], v[60:61], v[26:27], 1.0 op_sel_hi:[1,1,0]
	v_pk_mul_f32 v[42:43], v[42:43], v[58:59]
	v_pk_mul_f32 v[60:61], v[68:69], v[26:27]
	v_pk_mul_f32 v[68:69], v[70:71], v[24:25]
	v_pk_mul_f32 v[26:27], v[62:63], v[60:61]
	v_pk_mul_f32 v[24:25], v[64:65], v[68:69]
	s_waitcnt lgkmcnt(0)
	v_pk_mul_f32 v[26:27], v[52:53], v[26:27]
	v_pk_mul_f32 v[24:25], v[50:51], v[24:25]
	v_xor_b32_e32 v62, 0x80000000, v59
	v_add_f32_e32 v24, v24, v25
	v_add_f32_e32 v25, v26, v27
	v_add_f32_e32 v24, v24, v25
	v_add_f32_e32 v55, 0, v24
	ds_read_b128 v[24:27], v223 offset:43024
	v_xor_b32_e32 v63, 0x80000000, v58
	v_xor_b32_e32 v64, 0x80000000, v57
	v_xor_b32_e32 v65, 0x80000000, v56
	v_pk_mul_f32 v[40:41], v[40:41], v[56:57]
	v_pk_add_f32 v[56:57], v[38:39], -1.0 op_sel_hi:[1,0]
	v_pk_add_f32 v[58:59], v[36:37], -1.0 op_sel_hi:[1,0]
	v_pk_fma_f32 v[46:47], v[56:57], v[46:47], 1.0 op_sel_hi:[1,1,0]
	v_pk_fma_f32 v[44:45], v[58:59], v[44:45], 1.0 op_sel_hi:[1,1,0]
	v_pk_mul_f32 v[46:47], v[84:85], v[46:47]
	v_pk_mul_f32 v[44:45], v[86:87], v[44:45]
	v_pk_mul_f32 v[58:59], v[80:81], v[46:47]
	v_pk_mul_f32 v[56:57], v[82:83], v[44:45]
	s_waitcnt lgkmcnt(0)
	v_pk_mul_f32 v[26:27], v[26:27], v[58:59]
	v_pk_mul_f32 v[24:25], v[24:25], v[56:57]
	v_pk_mul_f32 v[50:51], v[90:91], v[54:55] op_sel_hi:[1,0]
	v_add_f32_e32 v24, v24, v25
	v_add_f32_e32 v25, v26, v27
	v_pk_mul_f32 v[52:53], v[92:93], v[54:55] op_sel_hi:[1,0]
	v_add_f32_e32 v24, v24, v25
	v_add_f32_e32 v55, v55, v24
	v_xor_b32_e32 v56, 0x80000000, v53
	v_xor_b32_e32 v57, 0x80000000, v52
	v_xor_b32_e32 v58, 0x80000000, v51
	v_xor_b32_e32 v59, 0x80000000, v50
	v_pk_mul_f32 v[36:37], v[36:37], v[50:51]
	v_lshl_add_u64 v[50:51], v[78:79], 0, s[30:31]
	v_cvt_pk_bf16_f32 v24, v68, v69
	v_cvt_pk_bf16_f32 v25, v60, v61
	v_cvt_pk_bf16_f32 v26, v44, v45
	v_cvt_pk_bf16_f32 v27, v46, v47
	global_store_dwordx4 v[50:51], v[24:27], off nt
	s_nop 1
	v_pk_mul_f32 v[38:39], v[38:39], v[52:53]
	v_lshl_add_u64 v[44:45], v[78:79], 0, s[34:35]
	v_cvt_pk_bf16_f32 v24, v65, v64
	v_cvt_pk_bf16_f32 v25, v63, v62
	v_cvt_pk_bf16_f32 v26, v59, v58
	v_cvt_pk_bf16_f32 v27, v57, v56
	global_store_dwordx4 v[44:45], v[24:27], off nt
	s_nop 1
	v_lshl_add_u64 v[44:45], v[78:79], 0, s[6:7]
	v_cvt_pk_bf16_f32 v24, v40, v41
	v_cvt_pk_bf16_f32 v25, v42, v43
	v_cvt_pk_bf16_f32 v26, v36, v37
	v_cvt_pk_bf16_f32 v27, v38, v39
	global_store_dwordx4 v[44:45], v[24:27], off nt
	s_nop 1
	ds_read_b128 v[24:27], v223 offset:41088
	ds_read_b128 v[36:39], v223 offset:41104
	ds_read_b128 v[40:43], v223 offset:43136
	v_pk_add_f32 v[44:45], v[34:35], -1.0 op_sel_hi:[1,0]
	v_pk_add_f32 v[46:47], v[32:33], -1.0 op_sel_hi:[1,0]
	s_waitcnt lgkmcnt(2)
	v_pk_fma_f32 v[26:27], v[44:45], v[26:27], 1.0 op_sel_hi:[1,1,0]
	v_pk_fma_f32 v[24:25], v[46:47], v[24:25], 1.0 op_sel_hi:[1,1,0]
	v_pk_mul_f32 v[12:13], v[12:13], v[26:27]
	v_pk_mul_f32 v[8:9], v[8:9], v[24:25]
	v_pk_mul_f32 v[0:1], v[0:1], v[12:13]
	v_pk_mul_f32 v[4:5], v[4:5], v[8:9]
	s_waitcnt lgkmcnt(0)
	v_pk_mul_f32 v[0:1], v[42:43], v[0:1]
	v_pk_mul_f32 v[4:5], v[40:41], v[4:5]
	v_add_f32_e32 v0, v0, v1
	v_add_f32_e32 v4, v4, v5
	v_pk_mul_f32 v[16:17], v[16:17], v[54:55] op_sel_hi:[1,0]
	v_add_f32_e32 v0, v4, v0
	v_add_f32_e32 v40, v55, v0
	v_xor_b32_e32 v41, 0x80000000, v17
	v_xor_b32_e32 v42, 0x80000000, v16
	v_pk_mul_f32 v[4:5], v[34:35], v[16:17]
	v_pk_mul_f32 v[0:1], v[22:23], v[54:55] op_sel_hi:[1,0]
	v_pk_mul_f32 v[22:23], v[18:19], v[54:55] op_sel_hi:[1,0]
	ds_read_b128 v[16:19], v223 offset:43152
	v_pk_add_f32 v[24:25], v[30:31], -1.0 op_sel_hi:[1,0]
	v_pk_add_f32 v[26:27], v[28:29], -1.0 op_sel_hi:[1,0]
	v_pk_fma_f32 v[24:25], v[24:25], v[38:39], 1.0 op_sel_hi:[1,1,0]
	v_pk_fma_f32 v[26:27], v[26:27], v[36:37], 1.0 op_sel_hi:[1,1,0]
	v_pk_mul_f32 v[14:15], v[14:15], v[24:25]
	v_pk_mul_f32 v[10:11], v[10:11], v[26:27]
	v_pk_mul_f32 v[2:3], v[2:3], v[14:15]
	v_pk_mul_f32 v[6:7], v[6:7], v[10:11]
	s_waitcnt lgkmcnt(0)
	v_pk_mul_f32 v[2:3], v[18:19], v[2:3]
	v_pk_mul_f32 v[6:7], v[16:17], v[6:7]
	v_pk_mul_f32 v[20:21], v[20:21], v[54:55] op_sel_hi:[1,0]
	v_add_f32_e32 v6, v6, v7
	v_add_f32_e32 v2, v2, v3
	v_xor_b32_e32 v43, 0x80000000, v21
	v_xor_b32_e32 v44, 0x80000000, v20
	v_pk_mul_f32 v[20:21], v[32:33], v[20:21]
	v_add_f32_e32 v2, v6, v2
	v_xor_b32_e32 v32, 0x80000000, v0
	v_pk_mul_f32 v[16:17], v[28:29], v[0:1]
	s_mov_b64 s[6:7], 0xc0
	v_cvt_pk_bf16_f32 v0, v8, v9
	v_add_f32_e32 v24, v40, v2
	v_xor_b32_e32 v25, 0x80000000, v23
	v_xor_b32_e32 v26, 0x80000000, v22
	v_xor_b32_e32 v27, 0x80000000, v1
	v_lshl_add_u64 v[18:19], v[78:79], 0, s[6:7]
	v_cvt_pk_bf16_f32 v1, v12, v13
	v_cvt_pk_bf16_f32 v2, v10, v11
	v_cvt_pk_bf16_f32 v3, v14, v15
	global_store_dwordx4 v[18:19], v[0:3], off nt
	s_nop 1
	s_mov_b64 s[6:7], 0x140
	v_cvt_pk_bf16_f32 v0, v44, v43
	v_pk_mul_f32 v[6:7], v[30:31], v[22:23]
	v_lshl_add_u64 v[8:9], v[78:79], 0, s[6:7]
	v_cvt_pk_bf16_f32 v1, v42, v41
	v_cvt_pk_bf16_f32 v2, v32, v27
	v_cvt_pk_bf16_f32 v3, v26, v25
	global_store_dwordx4 v[8:9], v[0:3], off nt
	s_nop 1
	s_mov_b64 s[6:7], 0x1c0
	v_cvt_pk_bf16_f32 v0, v20, v21
	v_lshl_add_u64 v[8:9], v[78:79], 0, s[6:7]
	v_cvt_pk_bf16_f32 v1, v4, v5
	v_cvt_pk_bf16_f32 v2, v16, v17
	v_cvt_pk_bf16_f32 v3, v6, v7
	global_store_dwordx4 v[8:9], v[0:3], off nt
	s_nop 1
	ds_bpermute_b32 v0, v131, v24
	s_waitcnt lgkmcnt(0)
	v_add_f32_e32 v0, v24, v0
	v_mov_b32_e32 v1, v0
	s_nop 1
	v_permlane32_swap_b32_e32 v0, v1
	s_and_saveexec_b64 s[46:47], s[44:45]
	s_cbranch_execz .LBB0_901
	v_add_f32_e32 v2, v0, v1
	v_lshlrev_b64 v[0:1], 5, v[66:67]
	v_lshl_add_u64 v[0:1], s[58:59], 0, v[0:1]
	global_store_dword v[0:1], v2, off
	s_branch .LBB0_901
